# c10 = c7 + hand-written residual-add epilogues (5 GEMM instances): one memory round trip per unit instead of two
# speedup vs baseline: 1.0017x; 1.0003x over previous
.LBB0_1056:
	s_andn2_b64 vcc, exec, s[2:3]
	v_lshlrev_b32_e32 v214, 12, v179
	v_lshl_add_u32 v214, v180, 1, v214
	v_lshlrev_b32_e32 v215, 2, v180
	s_lshl_b32 s11, s18, 20
	s_lshl_b32 s13, s19, 9
	s_add_u32 s11, s11, s13
	s_add_u32 s2, s6, s11
	s_addc_u32 s3, s7, 0
	s_lshr_b32 s11, s18, 4
	s_mul_i32 s11, s11, 0x12000
	s_lshl_b32 s13, s19, 10
	s_add_u32 s11, s11, s13
	s_add_u32 s18, s56, s11
	s_addc_u32 s19, s57, 0
	global_load_dwordx4 v[194:197], v215, s[18:19]
	global_load_dwordx4 v[198:201], v215, s[18:19] offset:16
	global_load_dwordx4 v[202:205], v215, s[18:19] offset:512
	global_load_dwordx4 v[206:209], v215, s[18:19] offset:528
	s_add_u32 s18, s2, 0x0
	s_addc_u32 s19, s3, 0
	global_load_dwordx4 v[130:133], v214, s[18:19]
	global_load_dwordx4 v[134:137], v214, s[18:19] offset:256
	s_add_u32 s18, s2, 0x10000
	s_addc_u32 s19, s3, 0
	global_load_dwordx4 v[138:141], v214, s[18:19]
	global_load_dwordx4 v[142:145], v214, s[18:19] offset:256
	s_add_u32 s18, s2, 0x20000
	s_addc_u32 s19, s3, 0
	global_load_dwordx4 v[146:149], v214, s[18:19]
	global_load_dwordx4 v[150:153], v214, s[18:19] offset:256
	s_add_u32 s18, s2, 0x30000
	s_addc_u32 s19, s3, 0
	global_load_dwordx4 v[154:157], v214, s[18:19]
	global_load_dwordx4 v[158:161], v214, s[18:19] offset:256
	s_add_u32 s18, s2, 0x80000
	s_addc_u32 s19, s3, 0
	global_load_dwordx4 v[166:169], v214, s[18:19]
	global_load_dwordx4 v[170:173], v214, s[18:19] offset:256
	s_add_u32 s18, s2, 0x90000
	s_addc_u32 s19, s3, 0
	global_load_dwordx4 v[186:189], v214, s[18:19]
	global_load_dwordx4 v[190:193], v214, s[18:19] offset:256
	s_waitcnt vmcnt(12)
	s_waitcnt vmcnt(11)
	v_cvt_f32_f16_e32 v210, v130
	v_cvt_f32_f16_sdwa v211, v130 dst_sel:DWORD dst_unused:UNUSED_PAD src0_sel:WORD_1
	v_cvt_f32_f16_e32 v212, v131
	v_cvt_f32_f16_sdwa v213, v131 dst_sel:DWORD dst_unused:UNUSED_PAD src0_sel:WORD_1
	v_pk_fma_f32 v[126:127], v[126:127], v[194:195], v[210:211]
	v_pk_fma_f32 v[128:129], v[128:129], v[196:197], v[212:213]
	v_cvt_f32_f16_e32 v210, v132
	v_cvt_f32_f16_sdwa v211, v132 dst_sel:DWORD dst_unused:UNUSED_PAD src0_sel:WORD_1
	v_cvt_f32_f16_e32 v212, v133
	v_cvt_f32_f16_sdwa v213, v133 dst_sel:DWORD dst_unused:UNUSED_PAD src0_sel:WORD_1
	v_pk_fma_f32 v[122:123], v[122:123], v[198:199], v[210:211]
	v_pk_fma_f32 v[124:125], v[124:125], v[200:201], v[212:213]
	v_cvt_pk_f16_f32 v130, v126, v127
	v_cvt_pk_f16_f32 v131, v128, v129
	v_cvt_pk_f16_f32 v132, v122, v123
	v_cvt_pk_f16_f32 v133, v124, v125
	s_add_u32 s18, s2, 0x0
	s_addc_u32 s19, s3, 0
	global_store_dwordx4 v214, v[130:133], s[18:19]
	s_waitcnt vmcnt(11)
	v_cvt_f32_f16_e32 v210, v134
	v_cvt_f32_f16_sdwa v211, v134 dst_sel:DWORD dst_unused:UNUSED_PAD src0_sel:WORD_1
	v_cvt_f32_f16_e32 v212, v135
	v_cvt_f32_f16_sdwa v213, v135 dst_sel:DWORD dst_unused:UNUSED_PAD src0_sel:WORD_1
	v_pk_fma_f32 v[110:111], v[110:111], v[202:203], v[210:211]
	v_pk_fma_f32 v[112:113], v[112:113], v[204:205], v[212:213]
	v_cvt_f32_f16_e32 v210, v136
	v_cvt_f32_f16_sdwa v211, v136 dst_sel:DWORD dst_unused:UNUSED_PAD src0_sel:WORD_1
	v_cvt_f32_f16_e32 v212, v137
	v_cvt_f32_f16_sdwa v213, v137 dst_sel:DWORD dst_unused:UNUSED_PAD src0_sel:WORD_1
	v_pk_fma_f32 v[106:107], v[106:107], v[206:207], v[210:211]
	v_pk_fma_f32 v[108:109], v[108:109], v[208:209], v[212:213]
	v_cvt_pk_f16_f32 v134, v110, v111
	v_cvt_pk_f16_f32 v135, v112, v113
	v_cvt_pk_f16_f32 v136, v106, v107
	v_cvt_pk_f16_f32 v137, v108, v109
	global_store_dwordx4 v214, v[134:137], s[18:19] offset:256
	s_nop 1
	s_add_u32 s18, s2, 0xa0000
	s_addc_u32 s19, s3, 0
	global_load_dwordx4 v[126:129], v214, s[18:19]
	global_load_dwordx4 v[122:125], v214, s[18:19] offset:256
	s_add_u32 s18, s2, 0xb0000
	s_addc_u32 s19, s3, 0
	global_load_dwordx4 v[110:113], v214, s[18:19]
	global_load_dwordx4 v[106:109], v214, s[18:19] offset:256
	s_waitcnt vmcnt(15)
	v_cvt_f32_f16_e32 v210, v138
	v_cvt_f32_f16_sdwa v211, v138 dst_sel:DWORD dst_unused:UNUSED_PAD src0_sel:WORD_1
	v_cvt_f32_f16_e32 v212, v139
	v_cvt_f32_f16_sdwa v213, v139 dst_sel:DWORD dst_unused:UNUSED_PAD src0_sel:WORD_1
	v_pk_fma_f32 v[118:119], v[118:119], v[194:195], v[210:211]
	v_pk_fma_f32 v[120:121], v[120:121], v[196:197], v[212:213]
	v_cvt_f32_f16_e32 v210, v140
	v_cvt_f32_f16_sdwa v211, v140 dst_sel:DWORD dst_unused:UNUSED_PAD src0_sel:WORD_1
	v_cvt_f32_f16_e32 v212, v141
	v_cvt_f32_f16_sdwa v213, v141 dst_sel:DWORD dst_unused:UNUSED_PAD src0_sel:WORD_1
	v_pk_fma_f32 v[114:115], v[114:115], v[198:199], v[210:211]
	v_pk_fma_f32 v[116:117], v[116:117], v[200:201], v[212:213]
	v_cvt_pk_f16_f32 v138, v118, v119
	v_cvt_pk_f16_f32 v139, v120, v121
	v_cvt_pk_f16_f32 v140, v114, v115
	v_cvt_pk_f16_f32 v141, v116, v117
	s_add_u32 s18, s2, 0x10000
	s_addc_u32 s19, s3, 0
	global_store_dwordx4 v214, v[138:141], s[18:19]
	s_waitcnt vmcnt(15)
	v_cvt_f32_f16_e32 v210, v142
	v_cvt_f32_f16_sdwa v211, v142 dst_sel:DWORD dst_unused:UNUSED_PAD src0_sel:WORD_1
	v_cvt_f32_f16_e32 v212, v143
	v_cvt_f32_f16_sdwa v213, v143 dst_sel:DWORD dst_unused:UNUSED_PAD src0_sel:WORD_1
	v_pk_fma_f32 v[102:103], v[102:103], v[202:203], v[210:211]
	v_pk_fma_f32 v[104:105], v[104:105], v[204:205], v[212:213]
	v_cvt_f32_f16_e32 v210, v144
	v_cvt_f32_f16_sdwa v211, v144 dst_sel:DWORD dst_unused:UNUSED_PAD src0_sel:WORD_1
	v_cvt_f32_f16_e32 v212, v145
	v_cvt_f32_f16_sdwa v213, v145 dst_sel:DWORD dst_unused:UNUSED_PAD src0_sel:WORD_1
	v_pk_fma_f32 v[98:99], v[98:99], v[206:207], v[210:211]
	v_pk_fma_f32 v[100:101], v[100:101], v[208:209], v[212:213]
	v_cvt_pk_f16_f32 v142, v102, v103
	v_cvt_pk_f16_f32 v143, v104, v105
	v_cvt_pk_f16_f32 v144, v98, v99
	v_cvt_pk_f16_f32 v145, v100, v101
	global_store_dwordx4 v214, v[142:145], s[18:19] offset:256
	s_waitcnt vmcnt(15)
	v_cvt_f32_f16_e32 v210, v146
	v_cvt_f32_f16_sdwa v211, v146 dst_sel:DWORD dst_unused:UNUSED_PAD src0_sel:WORD_1
	v_cvt_f32_f16_e32 v212, v147
	v_cvt_f32_f16_sdwa v213, v147 dst_sel:DWORD dst_unused:UNUSED_PAD src0_sel:WORD_1
	v_pk_fma_f32 v[94:95], v[94:95], v[194:195], v[210:211]
	v_pk_fma_f32 v[96:97], v[96:97], v[196:197], v[212:213]
	v_cvt_f32_f16_e32 v210, v148
	v_cvt_f32_f16_sdwa v211, v148 dst_sel:DWORD dst_unused:UNUSED_PAD src0_sel:WORD_1
	v_cvt_f32_f16_e32 v212, v149
	v_cvt_f32_f16_sdwa v213, v149 dst_sel:DWORD dst_unused:UNUSED_PAD src0_sel:WORD_1
	v_pk_fma_f32 v[90:91], v[90:91], v[198:199], v[210:211]
	v_pk_fma_f32 v[92:93], v[92:93], v[200:201], v[212:213]
	v_cvt_pk_f16_f32 v146, v94, v95
	v_cvt_pk_f16_f32 v147, v96, v97
	v_cvt_pk_f16_f32 v148, v90, v91
	v_cvt_pk_f16_f32 v149, v92, v93
	s_add_u32 s18, s2, 0x20000
	s_addc_u32 s19, s3, 0
	global_store_dwordx4 v214, v[146:149], s[18:19]
	s_waitcnt vmcnt(15)
	v_cvt_f32_f16_e32 v210, v150
	v_cvt_f32_f16_sdwa v211, v150 dst_sel:DWORD dst_unused:UNUSED_PAD src0_sel:WORD_1
	v_cvt_f32_f16_e32 v212, v151
	v_cvt_f32_f16_sdwa v213, v151 dst_sel:DWORD dst_unused:UNUSED_PAD src0_sel:WORD_1
	v_pk_fma_f32 v[82:83], v[82:83], v[202:203], v[210:211]
	v_pk_fma_f32 v[84:85], v[84:85], v[204:205], v[212:213]
	v_cvt_f32_f16_e32 v210, v152
	v_cvt_f32_f16_sdwa v211, v152 dst_sel:DWORD dst_unused:UNUSED_PAD src0_sel:WORD_1
	v_cvt_f32_f16_e32 v212, v153
	v_cvt_f32_f16_sdwa v213, v153 dst_sel:DWORD dst_unused:UNUSED_PAD src0_sel:WORD_1
	v_pk_fma_f32 v[74:75], v[74:75], v[206:207], v[210:211]
	v_pk_fma_f32 v[76:77], v[76:77], v[208:209], v[212:213]
	v_cvt_pk_f16_f32 v150, v82, v83
	v_cvt_pk_f16_f32 v151, v84, v85
	v_cvt_pk_f16_f32 v152, v74, v75
	v_cvt_pk_f16_f32 v153, v76, v77
	global_store_dwordx4 v214, v[150:153], s[18:19] offset:256
	s_waitcnt vmcnt(15)
	v_cvt_f32_f16_e32 v210, v154
	v_cvt_f32_f16_sdwa v211, v154 dst_sel:DWORD dst_unused:UNUSED_PAD src0_sel:WORD_1
	v_cvt_f32_f16_e32 v212, v155
	v_cvt_f32_f16_sdwa v213, v155 dst_sel:DWORD dst_unused:UNUSED_PAD src0_sel:WORD_1
	v_pk_fma_f32 v[86:87], v[86:87], v[194:195], v[210:211]
	v_pk_fma_f32 v[88:89], v[88:89], v[196:197], v[212:213]
	v_cvt_f32_f16_e32 v210, v156
	v_cvt_f32_f16_sdwa v211, v156 dst_sel:DWORD dst_unused:UNUSED_PAD src0_sel:WORD_1
	v_cvt_f32_f16_e32 v212, v157
	v_cvt_f32_f16_sdwa v213, v157 dst_sel:DWORD dst_unused:UNUSED_PAD src0_sel:WORD_1
	v_pk_fma_f32 v[78:79], v[78:79], v[198:199], v[210:211]
	v_pk_fma_f32 v[80:81], v[80:81], v[200:201], v[212:213]
	v_cvt_pk_f16_f32 v154, v86, v87
	v_cvt_pk_f16_f32 v155, v88, v89
	v_cvt_pk_f16_f32 v156, v78, v79
	v_cvt_pk_f16_f32 v157, v80, v81
	s_add_u32 s18, s2, 0x30000
	s_addc_u32 s19, s3, 0
	global_store_dwordx4 v214, v[154:157], s[18:19]
	s_waitcnt vmcnt(15)
	v_cvt_f32_f16_e32 v210, v158
	v_cvt_f32_f16_sdwa v211, v158 dst_sel:DWORD dst_unused:UNUSED_PAD src0_sel:WORD_1
	v_cvt_f32_f16_e32 v212, v159
	v_cvt_f32_f16_sdwa v213, v159 dst_sel:DWORD dst_unused:UNUSED_PAD src0_sel:WORD_1
	v_pk_fma_f32 v[70:71], v[70:71], v[202:203], v[210:211]
	v_pk_fma_f32 v[72:73], v[72:73], v[204:205], v[212:213]
	v_cvt_f32_f16_e32 v210, v160
	v_cvt_f32_f16_sdwa v211, v160 dst_sel:DWORD dst_unused:UNUSED_PAD src0_sel:WORD_1
	v_cvt_f32_f16_e32 v212, v161
	v_cvt_f32_f16_sdwa v213, v161 dst_sel:DWORD dst_unused:UNUSED_PAD src0_sel:WORD_1
	v_pk_fma_f32 v[66:67], v[66:67], v[206:207], v[210:211]
	v_pk_fma_f32 v[68:69], v[68:69], v[208:209], v[212:213]
	v_cvt_pk_f16_f32 v158, v70, v71
	v_cvt_pk_f16_f32 v159, v72, v73
	v_cvt_pk_f16_f32 v160, v66, v67
	v_cvt_pk_f16_f32 v161, v68, v69
	global_store_dwordx4 v214, v[158:161], s[18:19] offset:256
	s_waitcnt vmcnt(15)
	v_cvt_f32_f16_e32 v210, v166
	v_cvt_f32_f16_sdwa v211, v166 dst_sel:DWORD dst_unused:UNUSED_PAD src0_sel:WORD_1
	v_cvt_f32_f16_e32 v212, v167
	v_cvt_f32_f16_sdwa v213, v167 dst_sel:DWORD dst_unused:UNUSED_PAD src0_sel:WORD_1
	v_pk_fma_f32 v[62:63], v[62:63], v[194:195], v[210:211]
	v_pk_fma_f32 v[64:65], v[64:65], v[196:197], v[212:213]
	v_cvt_f32_f16_e32 v210, v168
	v_cvt_f32_f16_sdwa v211, v168 dst_sel:DWORD dst_unused:UNUSED_PAD src0_sel:WORD_1
	v_cvt_f32_f16_e32 v212, v169
	v_cvt_f32_f16_sdwa v213, v169 dst_sel:DWORD dst_unused:UNUSED_PAD src0_sel:WORD_1
	v_pk_fma_f32 v[58:59], v[58:59], v[198:199], v[210:211]
	v_pk_fma_f32 v[60:61], v[60:61], v[200:201], v[212:213]
	v_cvt_pk_f16_f32 v166, v62, v63
	v_cvt_pk_f16_f32 v167, v64, v65
	v_cvt_pk_f16_f32 v168, v58, v59
	v_cvt_pk_f16_f32 v169, v60, v61
	s_add_u32 s18, s2, 0x80000
	s_addc_u32 s19, s3, 0
	global_store_dwordx4 v214, v[166:169], s[18:19]
	s_waitcnt vmcnt(15)
	v_cvt_f32_f16_e32 v210, v170
	v_cvt_f32_f16_sdwa v211, v170 dst_sel:DWORD dst_unused:UNUSED_PAD src0_sel:WORD_1
	v_cvt_f32_f16_e32 v212, v171
	v_cvt_f32_f16_sdwa v213, v171 dst_sel:DWORD dst_unused:UNUSED_PAD src0_sel:WORD_1
	v_pk_fma_f32 v[54:55], v[54:55], v[202:203], v[210:211]
	v_pk_fma_f32 v[56:57], v[56:57], v[204:205], v[212:213]
	v_cvt_f32_f16_e32 v210, v172
	v_cvt_f32_f16_sdwa v211, v172 dst_sel:DWORD dst_unused:UNUSED_PAD src0_sel:WORD_1
	v_cvt_f32_f16_e32 v212, v173
	v_cvt_f32_f16_sdwa v213, v173 dst_sel:DWORD dst_unused:UNUSED_PAD src0_sel:WORD_1
	v_pk_fma_f32 v[50:51], v[50:51], v[206:207], v[210:211]
	v_pk_fma_f32 v[52:53], v[52:53], v[208:209], v[212:213]
	v_cvt_pk_f16_f32 v170, v54, v55
	v_cvt_pk_f16_f32 v171, v56, v57
	v_cvt_pk_f16_f32 v172, v50, v51
	v_cvt_pk_f16_f32 v173, v52, v53
	global_store_dwordx4 v214, v[170:173], s[18:19] offset:256
	s_waitcnt vmcnt(15)
	v_cvt_f32_f16_e32 v210, v186
	v_cvt_f32_f16_sdwa v211, v186 dst_sel:DWORD dst_unused:UNUSED_PAD src0_sel:WORD_1
	v_cvt_f32_f16_e32 v212, v187
	v_cvt_f32_f16_sdwa v213, v187 dst_sel:DWORD dst_unused:UNUSED_PAD src0_sel:WORD_1
	v_pk_fma_f32 v[46:47], v[46:47], v[194:195], v[210:211]
	v_pk_fma_f32 v[48:49], v[48:49], v[196:197], v[212:213]
	v_cvt_f32_f16_e32 v210, v188
	v_cvt_f32_f16_sdwa v211, v188 dst_sel:DWORD dst_unused:UNUSED_PAD src0_sel:WORD_1
	v_cvt_f32_f16_e32 v212, v189
	v_cvt_f32_f16_sdwa v213, v189 dst_sel:DWORD dst_unused:UNUSED_PAD src0_sel:WORD_1
	v_pk_fma_f32 v[42:43], v[42:43], v[198:199], v[210:211]
	v_pk_fma_f32 v[44:45], v[44:45], v[200:201], v[212:213]
	v_cvt_pk_f16_f32 v186, v46, v47
	v_cvt_pk_f16_f32 v187, v48, v49
	v_cvt_pk_f16_f32 v188, v42, v43
	v_cvt_pk_f16_f32 v189, v44, v45
	s_add_u32 s18, s2, 0x90000
	s_addc_u32 s19, s3, 0
	global_store_dwordx4 v214, v[186:189], s[18:19]
	s_waitcnt vmcnt(15)
	v_cvt_f32_f16_e32 v210, v190
	v_cvt_f32_f16_sdwa v211, v190 dst_sel:DWORD dst_unused:UNUSED_PAD src0_sel:WORD_1
	v_cvt_f32_f16_e32 v212, v191
	v_cvt_f32_f16_sdwa v213, v191 dst_sel:DWORD dst_unused:UNUSED_PAD src0_sel:WORD_1
	v_pk_fma_f32 v[38:39], v[38:39], v[202:203], v[210:211]
	v_pk_fma_f32 v[40:41], v[40:41], v[204:205], v[212:213]
	v_cvt_f32_f16_e32 v210, v192
	v_cvt_f32_f16_sdwa v211, v192 dst_sel:DWORD dst_unused:UNUSED_PAD src0_sel:WORD_1
	v_cvt_f32_f16_e32 v212, v193
	v_cvt_f32_f16_sdwa v213, v193 dst_sel:DWORD dst_unused:UNUSED_PAD src0_sel:WORD_1
	v_pk_fma_f32 v[34:35], v[34:35], v[206:207], v[210:211]
	v_pk_fma_f32 v[36:37], v[36:37], v[208:209], v[212:213]
	v_cvt_pk_f16_f32 v190, v38, v39
	v_cvt_pk_f16_f32 v191, v40, v41
	v_cvt_pk_f16_f32 v192, v34, v35
	v_cvt_pk_f16_f32 v193, v36, v37
	global_store_dwordx4 v214, v[190:193], s[18:19] offset:256
	s_waitcnt vmcnt(13)
	v_cvt_f32_f16_e32 v210, v126
	v_cvt_f32_f16_sdwa v211, v126 dst_sel:DWORD dst_unused:UNUSED_PAD src0_sel:WORD_1
	v_cvt_f32_f16_e32 v212, v127
	v_cvt_f32_f16_sdwa v213, v127 dst_sel:DWORD dst_unused:UNUSED_PAD src0_sel:WORD_1
	v_pk_fma_f32 v[30:31], v[30:31], v[194:195], v[210:211]
	v_pk_fma_f32 v[32:33], v[32:33], v[196:197], v[212:213]
	v_cvt_f32_f16_e32 v210, v128
	v_cvt_f32_f16_sdwa v211, v128 dst_sel:DWORD dst_unused:UNUSED_PAD src0_sel:WORD_1
	v_cvt_f32_f16_e32 v212, v129
	v_cvt_f32_f16_sdwa v213, v129 dst_sel:DWORD dst_unused:UNUSED_PAD src0_sel:WORD_1
	v_pk_fma_f32 v[26:27], v[26:27], v[198:199], v[210:211]
	v_pk_fma_f32 v[28:29], v[28:29], v[200:201], v[212:213]
	v_cvt_pk_f16_f32 v126, v30, v31
	v_cvt_pk_f16_f32 v127, v32, v33
	v_cvt_pk_f16_f32 v128, v26, v27
	v_cvt_pk_f16_f32 v129, v28, v29
	s_add_u32 s18, s2, 0xa0000
	s_addc_u32 s19, s3, 0
	global_store_dwordx4 v214, v[126:129], s[18:19]
	s_waitcnt vmcnt(13)
	v_cvt_f32_f16_e32 v210, v122
	v_cvt_f32_f16_sdwa v211, v122 dst_sel:DWORD dst_unused:UNUSED_PAD src0_sel:WORD_1
	v_cvt_f32_f16_e32 v212, v123
	v_cvt_f32_f16_sdwa v213, v123 dst_sel:DWORD dst_unused:UNUSED_PAD src0_sel:WORD_1
	v_pk_fma_f32 v[22:23], v[22:23], v[202:203], v[210:211]
	v_pk_fma_f32 v[24:25], v[24:25], v[204:205], v[212:213]
	v_cvt_f32_f16_e32 v210, v124
	v_cvt_f32_f16_sdwa v211, v124 dst_sel:DWORD dst_unused:UNUSED_PAD src0_sel:WORD_1
	v_cvt_f32_f16_e32 v212, v125
	v_cvt_f32_f16_sdwa v213, v125 dst_sel:DWORD dst_unused:UNUSED_PAD src0_sel:WORD_1
	v_pk_fma_f32 v[18:19], v[18:19], v[206:207], v[210:211]
	v_pk_fma_f32 v[20:21], v[20:21], v[208:209], v[212:213]
	v_cvt_pk_f16_f32 v122, v22, v23
	v_cvt_pk_f16_f32 v123, v24, v25
	v_cvt_pk_f16_f32 v124, v18, v19
	v_cvt_pk_f16_f32 v125, v20, v21
	global_store_dwordx4 v214, v[122:125], s[18:19] offset:256
	s_waitcnt vmcnt(13)
	v_cvt_f32_f16_e32 v210, v110
	v_cvt_f32_f16_sdwa v211, v110 dst_sel:DWORD dst_unused:UNUSED_PAD src0_sel:WORD_1
	v_cvt_f32_f16_e32 v212, v111
	v_cvt_f32_f16_sdwa v213, v111 dst_sel:DWORD dst_unused:UNUSED_PAD src0_sel:WORD_1
	v_pk_fma_f32 v[14:15], v[14:15], v[194:195], v[210:211]
	v_pk_fma_f32 v[16:17], v[16:17], v[196:197], v[212:213]
	v_cvt_f32_f16_e32 v210, v112
	v_cvt_f32_f16_sdwa v211, v112 dst_sel:DWORD dst_unused:UNUSED_PAD src0_sel:WORD_1
	v_cvt_f32_f16_e32 v212, v113
	v_cvt_f32_f16_sdwa v213, v113 dst_sel:DWORD dst_unused:UNUSED_PAD src0_sel:WORD_1
	v_pk_fma_f32 v[10:11], v[10:11], v[198:199], v[210:211]
	v_pk_fma_f32 v[12:13], v[12:13], v[200:201], v[212:213]
	v_cvt_pk_f16_f32 v110, v14, v15
	v_cvt_pk_f16_f32 v111, v16, v17
	v_cvt_pk_f16_f32 v112, v10, v11
	v_cvt_pk_f16_f32 v113, v12, v13
	s_add_u32 s18, s2, 0xb0000
	s_addc_u32 s19, s3, 0
	global_store_dwordx4 v214, v[110:113], s[18:19]
	s_waitcnt vmcnt(13)
	v_cvt_f32_f16_e32 v210, v106
	v_cvt_f32_f16_sdwa v211, v106 dst_sel:DWORD dst_unused:UNUSED_PAD src0_sel:WORD_1
	v_cvt_f32_f16_e32 v212, v107
	v_cvt_f32_f16_sdwa v213, v107 dst_sel:DWORD dst_unused:UNUSED_PAD src0_sel:WORD_1
	v_pk_fma_f32 v[6:7], v[6:7], v[202:203], v[210:211]
	v_pk_fma_f32 v[8:9], v[8:9], v[204:205], v[212:213]
	v_cvt_f32_f16_e32 v210, v108
	v_cvt_f32_f16_sdwa v211, v108 dst_sel:DWORD dst_unused:UNUSED_PAD src0_sel:WORD_1
	v_cvt_f32_f16_e32 v212, v109
	v_cvt_f32_f16_sdwa v213, v109 dst_sel:DWORD dst_unused:UNUSED_PAD src0_sel:WORD_1
	v_pk_fma_f32 v[2:3], v[2:3], v[206:207], v[210:211]
	v_pk_fma_f32 v[4:5], v[4:5], v[208:209], v[212:213]
	v_cvt_pk_f16_f32 v106, v6, v7
	v_cvt_pk_f16_f32 v107, v8, v9
	v_cvt_pk_f16_f32 v108, v2, v3
	v_cvt_pk_f16_f32 v109, v4, v5
	global_store_dwordx4 v214, v[106:109], s[18:19] offset:256
	s_mov_b64 s[2:3], -1
	s_cbranch_vccnz .LBB0_1045
	s_andn2_b64 vcc, exec, s[4:5]
	s_cbranch_vccnz .LBB0_1044
	s_barrier
	s_branch .LBB0_1044

.LBB0_1360:
	s_andn2_b64 vcc, exec, s[2:3]
	v_lshlrev_b32_e32 v214, 12, v179
	v_lshl_add_u32 v214, v180, 1, v214
	v_lshlrev_b32_e32 v215, 2, v180
	s_lshl_b32 s11, s18, 20
	s_lshl_b32 s13, s19, 9
	s_add_u32 s11, s11, s13
	s_add_u32 s2, s6, s11
	s_addc_u32 s3, s7, 0
	s_lshr_b32 s11, s18, 4
	s_mul_i32 s11, s11, 0x12000
	s_lshl_b32 s13, s19, 10
	s_add_u32 s11, s11, s13
	s_add_u32 s18, s56, s11
	s_addc_u32 s19, s57, 0
	global_load_dwordx4 v[194:197], v215, s[18:19]
	global_load_dwordx4 v[198:201], v215, s[18:19] offset:16
	global_load_dwordx4 v[202:205], v215, s[18:19] offset:512
	global_load_dwordx4 v[206:209], v215, s[18:19] offset:528
	s_add_u32 s18, s2, 0x0
	s_addc_u32 s19, s3, 0
	global_load_dwordx4 v[130:133], v214, s[18:19]
	global_load_dwordx4 v[134:137], v214, s[18:19] offset:256
	s_add_u32 s18, s2, 0x10000
	s_addc_u32 s19, s3, 0
	global_load_dwordx4 v[138:141], v214, s[18:19]
	global_load_dwordx4 v[142:145], v214, s[18:19] offset:256
	s_add_u32 s18, s2, 0x20000
	s_addc_u32 s19, s3, 0
	global_load_dwordx4 v[150:153], v214, s[18:19]
	global_load_dwordx4 v[154:157], v214, s[18:19] offset:256
	s_add_u32 s18, s2, 0x30000
	s_addc_u32 s19, s3, 0
	global_load_dwordx4 v[158:161], v214, s[18:19]
	global_load_dwordx4 v[162:165], v214, s[18:19] offset:256
	s_add_u32 s18, s2, 0x80000
	s_addc_u32 s19, s3, 0
	global_load_dwordx4 v[166:169], v214, s[18:19]
	global_load_dwordx4 v[170:173], v214, s[18:19] offset:256
	s_add_u32 s18, s2, 0x90000
	s_addc_u32 s19, s3, 0
	global_load_dwordx4 v[186:189], v214, s[18:19]
	global_load_dwordx4 v[190:193], v214, s[18:19] offset:256
	s_waitcnt vmcnt(12)
	v_pk_mul_f32 v[194:195], v[194:195], 0.5 op_sel_hi:[1,0]
	v_pk_mul_f32 v[196:197], v[196:197], 0.5 op_sel_hi:[1,0]
	v_pk_mul_f32 v[198:199], v[198:199], 0.5 op_sel_hi:[1,0]
	v_pk_mul_f32 v[200:201], v[200:201], 0.5 op_sel_hi:[1,0]
	v_pk_mul_f32 v[202:203], v[202:203], 0.5 op_sel_hi:[1,0]
	v_pk_mul_f32 v[204:205], v[204:205], 0.5 op_sel_hi:[1,0]
	v_pk_mul_f32 v[206:207], v[206:207], 0.5 op_sel_hi:[1,0]
	v_pk_mul_f32 v[208:209], v[208:209], 0.5 op_sel_hi:[1,0]
	s_waitcnt vmcnt(11)
	v_cvt_f32_f16_e32 v210, v130
	v_cvt_f32_f16_sdwa v211, v130 dst_sel:DWORD dst_unused:UNUSED_PAD src0_sel:WORD_1
	v_cvt_f32_f16_e32 v212, v131
	v_cvt_f32_f16_sdwa v213, v131 dst_sel:DWORD dst_unused:UNUSED_PAD src0_sel:WORD_1
	v_pk_fma_f32 v[126:127], v[126:127], v[194:195], v[210:211]
	v_pk_fma_f32 v[128:129], v[128:129], v[196:197], v[212:213]
	v_cvt_f32_f16_e32 v210, v132
	v_cvt_f32_f16_sdwa v211, v132 dst_sel:DWORD dst_unused:UNUSED_PAD src0_sel:WORD_1
	v_cvt_f32_f16_e32 v212, v133
	v_cvt_f32_f16_sdwa v213, v133 dst_sel:DWORD dst_unused:UNUSED_PAD src0_sel:WORD_1
	v_pk_fma_f32 v[122:123], v[122:123], v[198:199], v[210:211]
	v_pk_fma_f32 v[124:125], v[124:125], v[200:201], v[212:213]
	v_cvt_pk_f16_f32 v130, v126, v127
	v_cvt_pk_f16_f32 v131, v128, v129
	v_cvt_pk_f16_f32 v132, v122, v123
	v_cvt_pk_f16_f32 v133, v124, v125
	s_add_u32 s18, s2, 0x0
	s_addc_u32 s19, s3, 0
	global_store_dwordx4 v214, v[130:133], s[18:19]
	s_waitcnt vmcnt(11)
	v_cvt_f32_f16_e32 v210, v134
	v_cvt_f32_f16_sdwa v211, v134 dst_sel:DWORD dst_unused:UNUSED_PAD src0_sel:WORD_1
	v_cvt_f32_f16_e32 v212, v135
	v_cvt_f32_f16_sdwa v213, v135 dst_sel:DWORD dst_unused:UNUSED_PAD src0_sel:WORD_1
	v_pk_fma_f32 v[114:115], v[114:115], v[202:203], v[210:211]
	v_pk_fma_f32 v[116:117], v[116:117], v[204:205], v[212:213]
	v_cvt_f32_f16_e32 v210, v136
	v_cvt_f32_f16_sdwa v211, v136 dst_sel:DWORD dst_unused:UNUSED_PAD src0_sel:WORD_1
	v_cvt_f32_f16_e32 v212, v137
	v_cvt_f32_f16_sdwa v213, v137 dst_sel:DWORD dst_unused:UNUSED_PAD src0_sel:WORD_1
	v_pk_fma_f32 v[106:107], v[106:107], v[206:207], v[210:211]
	v_pk_fma_f32 v[108:109], v[108:109], v[208:209], v[212:213]
	v_cvt_pk_f16_f32 v134, v114, v115
	v_cvt_pk_f16_f32 v135, v116, v117
	v_cvt_pk_f16_f32 v136, v106, v107
	v_cvt_pk_f16_f32 v137, v108, v109
	global_store_dwordx4 v214, v[134:137], s[18:19] offset:256
	s_nop 1
	s_add_u32 s18, s2, 0xa0000
	s_addc_u32 s19, s3, 0
	global_load_dwordx4 v[126:129], v214, s[18:19]
	global_load_dwordx4 v[122:125], v214, s[18:19] offset:256
	s_add_u32 s18, s2, 0xb0000
	s_addc_u32 s19, s3, 0
	global_load_dwordx4 v[114:117], v214, s[18:19]
	global_load_dwordx4 v[106:109], v214, s[18:19] offset:256
	s_waitcnt vmcnt(15)
	v_cvt_f32_f16_e32 v210, v138
	v_cvt_f32_f16_sdwa v211, v138 dst_sel:DWORD dst_unused:UNUSED_PAD src0_sel:WORD_1
	v_cvt_f32_f16_e32 v212, v139
	v_cvt_f32_f16_sdwa v213, v139 dst_sel:DWORD dst_unused:UNUSED_PAD src0_sel:WORD_1
	v_pk_fma_f32 v[118:119], v[118:119], v[194:195], v[210:211]
	v_pk_fma_f32 v[120:121], v[120:121], v[196:197], v[212:213]
	v_cvt_f32_f16_e32 v210, v140
	v_cvt_f32_f16_sdwa v211, v140 dst_sel:DWORD dst_unused:UNUSED_PAD src0_sel:WORD_1
	v_cvt_f32_f16_e32 v212, v141
	v_cvt_f32_f16_sdwa v213, v141 dst_sel:DWORD dst_unused:UNUSED_PAD src0_sel:WORD_1
	v_pk_fma_f32 v[110:111], v[110:111], v[198:199], v[210:211]
	v_pk_fma_f32 v[112:113], v[112:113], v[200:201], v[212:213]
	v_cvt_pk_f16_f32 v138, v118, v119
	v_cvt_pk_f16_f32 v139, v120, v121
	v_cvt_pk_f16_f32 v140, v110, v111
	v_cvt_pk_f16_f32 v141, v112, v113
	s_add_u32 s18, s2, 0x10000
	s_addc_u32 s19, s3, 0
	global_store_dwordx4 v214, v[138:141], s[18:19]
	s_waitcnt vmcnt(15)
	v_cvt_f32_f16_e32 v210, v142
	v_cvt_f32_f16_sdwa v211, v142 dst_sel:DWORD dst_unused:UNUSED_PAD src0_sel:WORD_1
	v_cvt_f32_f16_e32 v212, v143
	v_cvt_f32_f16_sdwa v213, v143 dst_sel:DWORD dst_unused:UNUSED_PAD src0_sel:WORD_1
	v_pk_fma_f32 v[102:103], v[102:103], v[202:203], v[210:211]
	v_pk_fma_f32 v[104:105], v[104:105], v[204:205], v[212:213]
	v_cvt_f32_f16_e32 v210, v144
	v_cvt_f32_f16_sdwa v211, v144 dst_sel:DWORD dst_unused:UNUSED_PAD src0_sel:WORD_1
	v_cvt_f32_f16_e32 v212, v145
	v_cvt_f32_f16_sdwa v213, v145 dst_sel:DWORD dst_unused:UNUSED_PAD src0_sel:WORD_1
	v_pk_fma_f32 v[98:99], v[98:99], v[206:207], v[210:211]
	v_pk_fma_f32 v[100:101], v[100:101], v[208:209], v[212:213]
	v_cvt_pk_f16_f32 v142, v102, v103
	v_cvt_pk_f16_f32 v143, v104, v105
	v_cvt_pk_f16_f32 v144, v98, v99
	v_cvt_pk_f16_f32 v145, v100, v101
	global_store_dwordx4 v214, v[142:145], s[18:19] offset:256
	s_waitcnt vmcnt(15)
	v_cvt_f32_f16_e32 v210, v150
	v_cvt_f32_f16_sdwa v211, v150 dst_sel:DWORD dst_unused:UNUSED_PAD src0_sel:WORD_1
	v_cvt_f32_f16_e32 v212, v151
	v_cvt_f32_f16_sdwa v213, v151 dst_sel:DWORD dst_unused:UNUSED_PAD src0_sel:WORD_1
	v_pk_fma_f32 v[94:95], v[94:95], v[194:195], v[210:211]
	v_pk_fma_f32 v[96:97], v[96:97], v[196:197], v[212:213]
	v_cvt_f32_f16_e32 v210, v152
	v_cvt_f32_f16_sdwa v211, v152 dst_sel:DWORD dst_unused:UNUSED_PAD src0_sel:WORD_1
	v_cvt_f32_f16_e32 v212, v153
	v_cvt_f32_f16_sdwa v213, v153 dst_sel:DWORD dst_unused:UNUSED_PAD src0_sel:WORD_1
	v_pk_fma_f32 v[90:91], v[90:91], v[198:199], v[210:211]
	v_pk_fma_f32 v[92:93], v[92:93], v[200:201], v[212:213]
	v_cvt_pk_f16_f32 v150, v94, v95
	v_cvt_pk_f16_f32 v151, v96, v97
	v_cvt_pk_f16_f32 v152, v90, v91
	v_cvt_pk_f16_f32 v153, v92, v93
	s_add_u32 s18, s2, 0x20000
	s_addc_u32 s19, s3, 0
	global_store_dwordx4 v214, v[150:153], s[18:19]
	s_waitcnt vmcnt(15)
	v_cvt_f32_f16_e32 v210, v154
	v_cvt_f32_f16_sdwa v211, v154 dst_sel:DWORD dst_unused:UNUSED_PAD src0_sel:WORD_1
	v_cvt_f32_f16_e32 v212, v155
	v_cvt_f32_f16_sdwa v213, v155 dst_sel:DWORD dst_unused:UNUSED_PAD src0_sel:WORD_1
	v_pk_fma_f32 v[82:83], v[82:83], v[202:203], v[210:211]
	v_pk_fma_f32 v[84:85], v[84:85], v[204:205], v[212:213]
	v_cvt_f32_f16_e32 v210, v156
	v_cvt_f32_f16_sdwa v211, v156 dst_sel:DWORD dst_unused:UNUSED_PAD src0_sel:WORD_1
	v_cvt_f32_f16_e32 v212, v157
	v_cvt_f32_f16_sdwa v213, v157 dst_sel:DWORD dst_unused:UNUSED_PAD src0_sel:WORD_1
	v_pk_fma_f32 v[74:75], v[74:75], v[206:207], v[210:211]
	v_pk_fma_f32 v[76:77], v[76:77], v[208:209], v[212:213]
	v_cvt_pk_f16_f32 v154, v82, v83
	v_cvt_pk_f16_f32 v155, v84, v85
	v_cvt_pk_f16_f32 v156, v74, v75
	v_cvt_pk_f16_f32 v157, v76, v77
	global_store_dwordx4 v214, v[154:157], s[18:19] offset:256
	s_waitcnt vmcnt(15)
	v_cvt_f32_f16_e32 v210, v158
	v_cvt_f32_f16_sdwa v211, v158 dst_sel:DWORD dst_unused:UNUSED_PAD src0_sel:WORD_1
	v_cvt_f32_f16_e32 v212, v159
	v_cvt_f32_f16_sdwa v213, v159 dst_sel:DWORD dst_unused:UNUSED_PAD src0_sel:WORD_1
	v_pk_fma_f32 v[86:87], v[86:87], v[194:195], v[210:211]
	v_pk_fma_f32 v[88:89], v[88:89], v[196:197], v[212:213]
	v_cvt_f32_f16_e32 v210, v160
	v_cvt_f32_f16_sdwa v211, v160 dst_sel:DWORD dst_unused:UNUSED_PAD src0_sel:WORD_1
	v_cvt_f32_f16_e32 v212, v161
	v_cvt_f32_f16_sdwa v213, v161 dst_sel:DWORD dst_unused:UNUSED_PAD src0_sel:WORD_1
	v_pk_fma_f32 v[78:79], v[78:79], v[198:199], v[210:211]
	v_pk_fma_f32 v[80:81], v[80:81], v[200:201], v[212:213]
	v_cvt_pk_f16_f32 v158, v86, v87
	v_cvt_pk_f16_f32 v159, v88, v89
	v_cvt_pk_f16_f32 v160, v78, v79
	v_cvt_pk_f16_f32 v161, v80, v81
	s_add_u32 s18, s2, 0x30000
	s_addc_u32 s19, s3, 0
	global_store_dwordx4 v214, v[158:161], s[18:19]
	s_waitcnt vmcnt(15)
	v_cvt_f32_f16_e32 v210, v162
	v_cvt_f32_f16_sdwa v211, v162 dst_sel:DWORD dst_unused:UNUSED_PAD src0_sel:WORD_1
	v_cvt_f32_f16_e32 v212, v163
	v_cvt_f32_f16_sdwa v213, v163 dst_sel:DWORD dst_unused:UNUSED_PAD src0_sel:WORD_1
	v_pk_fma_f32 v[70:71], v[70:71], v[202:203], v[210:211]
	v_pk_fma_f32 v[72:73], v[72:73], v[204:205], v[212:213]
	v_cvt_f32_f16_e32 v210, v164
	v_cvt_f32_f16_sdwa v211, v164 dst_sel:DWORD dst_unused:UNUSED_PAD src0_sel:WORD_1
	v_cvt_f32_f16_e32 v212, v165
	v_cvt_f32_f16_sdwa v213, v165 dst_sel:DWORD dst_unused:UNUSED_PAD src0_sel:WORD_1
	v_pk_fma_f32 v[66:67], v[66:67], v[206:207], v[210:211]
	v_pk_fma_f32 v[68:69], v[68:69], v[208:209], v[212:213]
	v_cvt_pk_f16_f32 v162, v70, v71
	v_cvt_pk_f16_f32 v163, v72, v73
	v_cvt_pk_f16_f32 v164, v66, v67
	v_cvt_pk_f16_f32 v165, v68, v69
	global_store_dwordx4 v214, v[162:165], s[18:19] offset:256
	s_waitcnt vmcnt(15)
	v_cvt_f32_f16_e32 v210, v166
	v_cvt_f32_f16_sdwa v211, v166 dst_sel:DWORD dst_unused:UNUSED_PAD src0_sel:WORD_1
	v_cvt_f32_f16_e32 v212, v167
	v_cvt_f32_f16_sdwa v213, v167 dst_sel:DWORD dst_unused:UNUSED_PAD src0_sel:WORD_1
	v_pk_fma_f32 v[62:63], v[62:63], v[194:195], v[210:211]
	v_pk_fma_f32 v[64:65], v[64:65], v[196:197], v[212:213]
	v_cvt_f32_f16_e32 v210, v168
	v_cvt_f32_f16_sdwa v211, v168 dst_sel:DWORD dst_unused:UNUSED_PAD src0_sel:WORD_1
	v_cvt_f32_f16_e32 v212, v169
	v_cvt_f32_f16_sdwa v213, v169 dst_sel:DWORD dst_unused:UNUSED_PAD src0_sel:WORD_1
	v_pk_fma_f32 v[58:59], v[58:59], v[198:199], v[210:211]
	v_pk_fma_f32 v[60:61], v[60:61], v[200:201], v[212:213]
	v_cvt_pk_f16_f32 v166, v62, v63
	v_cvt_pk_f16_f32 v167, v64, v65
	v_cvt_pk_f16_f32 v168, v58, v59
	v_cvt_pk_f16_f32 v169, v60, v61
	s_add_u32 s18, s2, 0x80000
	s_addc_u32 s19, s3, 0
	global_store_dwordx4 v214, v[166:169], s[18:19]
	s_waitcnt vmcnt(15)
	v_cvt_f32_f16_e32 v210, v170
	v_cvt_f32_f16_sdwa v211, v170 dst_sel:DWORD dst_unused:UNUSED_PAD src0_sel:WORD_1
	v_cvt_f32_f16_e32 v212, v171
	v_cvt_f32_f16_sdwa v213, v171 dst_sel:DWORD dst_unused:UNUSED_PAD src0_sel:WORD_1
	v_pk_fma_f32 v[54:55], v[54:55], v[202:203], v[210:211]
	v_pk_fma_f32 v[56:57], v[56:57], v[204:205], v[212:213]
	v_cvt_f32_f16_e32 v210, v172
	v_cvt_f32_f16_sdwa v211, v172 dst_sel:DWORD dst_unused:UNUSED_PAD src0_sel:WORD_1
	v_cvt_f32_f16_e32 v212, v173
	v_cvt_f32_f16_sdwa v213, v173 dst_sel:DWORD dst_unused:UNUSED_PAD src0_sel:WORD_1
	v_pk_fma_f32 v[50:51], v[50:51], v[206:207], v[210:211]
	v_pk_fma_f32 v[52:53], v[52:53], v[208:209], v[212:213]
	v_cvt_pk_f16_f32 v170, v54, v55
	v_cvt_pk_f16_f32 v171, v56, v57
	v_cvt_pk_f16_f32 v172, v50, v51
	v_cvt_pk_f16_f32 v173, v52, v53
	global_store_dwordx4 v214, v[170:173], s[18:19] offset:256
	s_waitcnt vmcnt(15)
	v_cvt_f32_f16_e32 v210, v186
	v_cvt_f32_f16_sdwa v211, v186 dst_sel:DWORD dst_unused:UNUSED_PAD src0_sel:WORD_1
	v_cvt_f32_f16_e32 v212, v187
	v_cvt_f32_f16_sdwa v213, v187 dst_sel:DWORD dst_unused:UNUSED_PAD src0_sel:WORD_1
	v_pk_fma_f32 v[46:47], v[46:47], v[194:195], v[210:211]
	v_pk_fma_f32 v[48:49], v[48:49], v[196:197], v[212:213]
	v_cvt_f32_f16_e32 v210, v188
	v_cvt_f32_f16_sdwa v211, v188 dst_sel:DWORD dst_unused:UNUSED_PAD src0_sel:WORD_1
	v_cvt_f32_f16_e32 v212, v189
	v_cvt_f32_f16_sdwa v213, v189 dst_sel:DWORD dst_unused:UNUSED_PAD src0_sel:WORD_1
	v_pk_fma_f32 v[42:43], v[42:43], v[198:199], v[210:211]
	v_pk_fma_f32 v[44:45], v[44:45], v[200:201], v[212:213]
	v_cvt_pk_f16_f32 v186, v46, v47
	v_cvt_pk_f16_f32 v187, v48, v49
	v_cvt_pk_f16_f32 v188, v42, v43
	v_cvt_pk_f16_f32 v189, v44, v45
	s_add_u32 s18, s2, 0x90000
	s_addc_u32 s19, s3, 0
	global_store_dwordx4 v214, v[186:189], s[18:19]
	s_waitcnt vmcnt(15)
	v_cvt_f32_f16_e32 v210, v190
	v_cvt_f32_f16_sdwa v211, v190 dst_sel:DWORD dst_unused:UNUSED_PAD src0_sel:WORD_1
	v_cvt_f32_f16_e32 v212, v191
	v_cvt_f32_f16_sdwa v213, v191 dst_sel:DWORD dst_unused:UNUSED_PAD src0_sel:WORD_1
	v_pk_fma_f32 v[38:39], v[38:39], v[202:203], v[210:211]
	v_pk_fma_f32 v[40:41], v[40:41], v[204:205], v[212:213]
	v_cvt_f32_f16_e32 v210, v192
	v_cvt_f32_f16_sdwa v211, v192 dst_sel:DWORD dst_unused:UNUSED_PAD src0_sel:WORD_1
	v_cvt_f32_f16_e32 v212, v193
	v_cvt_f32_f16_sdwa v213, v193 dst_sel:DWORD dst_unused:UNUSED_PAD src0_sel:WORD_1
	v_pk_fma_f32 v[34:35], v[34:35], v[206:207], v[210:211]
	v_pk_fma_f32 v[36:37], v[36:37], v[208:209], v[212:213]
	v_cvt_pk_f16_f32 v190, v38, v39
	v_cvt_pk_f16_f32 v191, v40, v41
	v_cvt_pk_f16_f32 v192, v34, v35
	v_cvt_pk_f16_f32 v193, v36, v37
	global_store_dwordx4 v214, v[190:193], s[18:19] offset:256
	s_waitcnt vmcnt(13)
	v_cvt_f32_f16_e32 v210, v126
	v_cvt_f32_f16_sdwa v211, v126 dst_sel:DWORD dst_unused:UNUSED_PAD src0_sel:WORD_1
	v_cvt_f32_f16_e32 v212, v127
	v_cvt_f32_f16_sdwa v213, v127 dst_sel:DWORD dst_unused:UNUSED_PAD src0_sel:WORD_1
	v_pk_fma_f32 v[30:31], v[30:31], v[194:195], v[210:211]
	v_pk_fma_f32 v[32:33], v[32:33], v[196:197], v[212:213]
	v_cvt_f32_f16_e32 v210, v128
	v_cvt_f32_f16_sdwa v211, v128 dst_sel:DWORD dst_unused:UNUSED_PAD src0_sel:WORD_1
	v_cvt_f32_f16_e32 v212, v129
	v_cvt_f32_f16_sdwa v213, v129 dst_sel:DWORD dst_unused:UNUSED_PAD src0_sel:WORD_1
	v_pk_fma_f32 v[26:27], v[26:27], v[198:199], v[210:211]
	v_pk_fma_f32 v[28:29], v[28:29], v[200:201], v[212:213]
	v_cvt_pk_f16_f32 v126, v30, v31
	v_cvt_pk_f16_f32 v127, v32, v33
	v_cvt_pk_f16_f32 v128, v26, v27
	v_cvt_pk_f16_f32 v129, v28, v29
	s_add_u32 s18, s2, 0xa0000
	s_addc_u32 s19, s3, 0
	global_store_dwordx4 v214, v[126:129], s[18:19]
	s_waitcnt vmcnt(13)
	v_cvt_f32_f16_e32 v210, v122
	v_cvt_f32_f16_sdwa v211, v122 dst_sel:DWORD dst_unused:UNUSED_PAD src0_sel:WORD_1
	v_cvt_f32_f16_e32 v212, v123
	v_cvt_f32_f16_sdwa v213, v123 dst_sel:DWORD dst_unused:UNUSED_PAD src0_sel:WORD_1
	v_pk_fma_f32 v[22:23], v[22:23], v[202:203], v[210:211]
	v_pk_fma_f32 v[24:25], v[24:25], v[204:205], v[212:213]
	v_cvt_f32_f16_e32 v210, v124
	v_cvt_f32_f16_sdwa v211, v124 dst_sel:DWORD dst_unused:UNUSED_PAD src0_sel:WORD_1
	v_cvt_f32_f16_e32 v212, v125
	v_cvt_f32_f16_sdwa v213, v125 dst_sel:DWORD dst_unused:UNUSED_PAD src0_sel:WORD_1
	v_pk_fma_f32 v[18:19], v[18:19], v[206:207], v[210:211]
	v_pk_fma_f32 v[20:21], v[20:21], v[208:209], v[212:213]
	v_cvt_pk_f16_f32 v122, v22, v23
	v_cvt_pk_f16_f32 v123, v24, v25
	v_cvt_pk_f16_f32 v124, v18, v19
	v_cvt_pk_f16_f32 v125, v20, v21
	global_store_dwordx4 v214, v[122:125], s[18:19] offset:256
	s_waitcnt vmcnt(13)
	v_cvt_f32_f16_e32 v210, v114
	v_cvt_f32_f16_sdwa v211, v114 dst_sel:DWORD dst_unused:UNUSED_PAD src0_sel:WORD_1
	v_cvt_f32_f16_e32 v212, v115
	v_cvt_f32_f16_sdwa v213, v115 dst_sel:DWORD dst_unused:UNUSED_PAD src0_sel:WORD_1
	v_pk_fma_f32 v[14:15], v[14:15], v[194:195], v[210:211]
	v_pk_fma_f32 v[16:17], v[16:17], v[196:197], v[212:213]
	v_cvt_f32_f16_e32 v210, v116
	v_cvt_f32_f16_sdwa v211, v116 dst_sel:DWORD dst_unused:UNUSED_PAD src0_sel:WORD_1
	v_cvt_f32_f16_e32 v212, v117
	v_cvt_f32_f16_sdwa v213, v117 dst_sel:DWORD dst_unused:UNUSED_PAD src0_sel:WORD_1
	v_pk_fma_f32 v[10:11], v[10:11], v[198:199], v[210:211]
	v_pk_fma_f32 v[12:13], v[12:13], v[200:201], v[212:213]
	v_cvt_pk_f16_f32 v114, v14, v15
	v_cvt_pk_f16_f32 v115, v16, v17
	v_cvt_pk_f16_f32 v116, v10, v11
	v_cvt_pk_f16_f32 v117, v12, v13
	s_add_u32 s18, s2, 0xb0000
	s_addc_u32 s19, s3, 0
	global_store_dwordx4 v214, v[114:117], s[18:19]
	s_waitcnt vmcnt(13)
	v_cvt_f32_f16_e32 v210, v106
	v_cvt_f32_f16_sdwa v211, v106 dst_sel:DWORD dst_unused:UNUSED_PAD src0_sel:WORD_1
	v_cvt_f32_f16_e32 v212, v107
	v_cvt_f32_f16_sdwa v213, v107 dst_sel:DWORD dst_unused:UNUSED_PAD src0_sel:WORD_1
	v_pk_fma_f32 v[6:7], v[6:7], v[202:203], v[210:211]
	v_pk_fma_f32 v[8:9], v[8:9], v[204:205], v[212:213]
	v_cvt_f32_f16_e32 v210, v108
	v_cvt_f32_f16_sdwa v211, v108 dst_sel:DWORD dst_unused:UNUSED_PAD src0_sel:WORD_1
	v_cvt_f32_f16_e32 v212, v109
	v_cvt_f32_f16_sdwa v213, v109 dst_sel:DWORD dst_unused:UNUSED_PAD src0_sel:WORD_1
	v_pk_fma_f32 v[2:3], v[2:3], v[206:207], v[210:211]
	v_pk_fma_f32 v[4:5], v[4:5], v[208:209], v[212:213]
	v_cvt_pk_f16_f32 v106, v6, v7
	v_cvt_pk_f16_f32 v107, v8, v9
	v_cvt_pk_f16_f32 v108, v2, v3
	v_cvt_pk_f16_f32 v109, v4, v5
	global_store_dwordx4 v214, v[106:109], s[18:19] offset:256
	s_mov_b64 s[2:3], -1
	s_cbranch_vccnz .LBB0_1349
	s_andn2_b64 vcc, exec, s[4:5]
	s_cbranch_vccnz .LBB0_1348
	s_barrier
	s_branch .LBB0_1348

.LBB0_2413:
	s_andn2_b64 vcc, exec, s[2:3]
	v_lshlrev_b32_e32 v214, 12, v179
	v_lshl_add_u32 v214, v180, 1, v214
	v_lshlrev_b32_e32 v215, 2, v180
	s_lshl_b32 s15, s22, 20
	s_lshl_b32 s17, s23, 9
	s_add_u32 s15, s15, s17
	s_add_u32 s2, s6, s15
	s_addc_u32 s3, s7, 0
	s_lshr_b32 s15, s22, 4
	s_mul_i32 s15, s15, 0x12000
	s_lshl_b32 s17, s23, 10
	s_add_u32 s15, s15, s17
	s_add_u32 s22, s62, s15
	s_addc_u32 s23, s63, 0
	global_load_dwordx4 v[194:197], v215, s[22:23]
	global_load_dwordx4 v[198:201], v215, s[22:23] offset:16
	global_load_dwordx4 v[202:205], v215, s[22:23] offset:512
	global_load_dwordx4 v[206:209], v215, s[22:23] offset:528
	s_add_u32 s22, s2, 0x0
	s_addc_u32 s23, s3, 0
	global_load_dwordx4 v[130:133], v214, s[22:23]
	global_load_dwordx4 v[134:137], v214, s[22:23] offset:256
	s_add_u32 s22, s2, 0x10000
	s_addc_u32 s23, s3, 0
	global_load_dwordx4 v[138:141], v214, s[22:23]
	global_load_dwordx4 v[142:145], v214, s[22:23] offset:256
	s_add_u32 s22, s2, 0x20000
	s_addc_u32 s23, s3, 0
	global_load_dwordx4 v[146:149], v214, s[22:23]
	global_load_dwordx4 v[150:153], v214, s[22:23] offset:256
	s_add_u32 s22, s2, 0x30000
	s_addc_u32 s23, s3, 0
	global_load_dwordx4 v[154:157], v214, s[22:23]
	global_load_dwordx4 v[158:161], v214, s[22:23] offset:256
	s_add_u32 s22, s2, 0x80000
	s_addc_u32 s23, s3, 0
	global_load_dwordx4 v[166:169], v214, s[22:23]
	global_load_dwordx4 v[170:173], v214, s[22:23] offset:256
	s_add_u32 s22, s2, 0x90000
	s_addc_u32 s23, s3, 0
	global_load_dwordx4 v[186:189], v214, s[22:23]
	global_load_dwordx4 v[190:193], v214, s[22:23] offset:256
	s_waitcnt vmcnt(12)
	s_waitcnt vmcnt(11)
	v_cvt_f32_f16_e32 v210, v130
	v_cvt_f32_f16_sdwa v211, v130 dst_sel:DWORD dst_unused:UNUSED_PAD src0_sel:WORD_1
	v_cvt_f32_f16_e32 v212, v131
	v_cvt_f32_f16_sdwa v213, v131 dst_sel:DWORD dst_unused:UNUSED_PAD src0_sel:WORD_1
	v_pk_fma_f32 v[126:127], v[126:127], v[194:195], v[210:211]
	v_pk_fma_f32 v[128:129], v[128:129], v[196:197], v[212:213]
	v_cvt_f32_f16_e32 v210, v132
	v_cvt_f32_f16_sdwa v211, v132 dst_sel:DWORD dst_unused:UNUSED_PAD src0_sel:WORD_1
	v_cvt_f32_f16_e32 v212, v133
	v_cvt_f32_f16_sdwa v213, v133 dst_sel:DWORD dst_unused:UNUSED_PAD src0_sel:WORD_1
	v_pk_fma_f32 v[122:123], v[122:123], v[198:199], v[210:211]
	v_pk_fma_f32 v[124:125], v[124:125], v[200:201], v[212:213]
	v_cvt_pk_f16_f32 v130, v126, v127
	v_cvt_pk_f16_f32 v131, v128, v129
	v_cvt_pk_f16_f32 v132, v122, v123
	v_cvt_pk_f16_f32 v133, v124, v125
	s_add_u32 s22, s2, 0x0
	s_addc_u32 s23, s3, 0
	global_store_dwordx4 v214, v[130:133], s[22:23]
	s_waitcnt vmcnt(11)
	v_cvt_f32_f16_e32 v210, v134
	v_cvt_f32_f16_sdwa v211, v134 dst_sel:DWORD dst_unused:UNUSED_PAD src0_sel:WORD_1
	v_cvt_f32_f16_e32 v212, v135
	v_cvt_f32_f16_sdwa v213, v135 dst_sel:DWORD dst_unused:UNUSED_PAD src0_sel:WORD_1
	v_pk_fma_f32 v[110:111], v[110:111], v[202:203], v[210:211]
	v_pk_fma_f32 v[112:113], v[112:113], v[204:205], v[212:213]
	v_cvt_f32_f16_e32 v210, v136
	v_cvt_f32_f16_sdwa v211, v136 dst_sel:DWORD dst_unused:UNUSED_PAD src0_sel:WORD_1
	v_cvt_f32_f16_e32 v212, v137
	v_cvt_f32_f16_sdwa v213, v137 dst_sel:DWORD dst_unused:UNUSED_PAD src0_sel:WORD_1
	v_pk_fma_f32 v[106:107], v[106:107], v[206:207], v[210:211]
	v_pk_fma_f32 v[108:109], v[108:109], v[208:209], v[212:213]
	v_cvt_pk_f16_f32 v134, v110, v111
	v_cvt_pk_f16_f32 v135, v112, v113
	v_cvt_pk_f16_f32 v136, v106, v107
	v_cvt_pk_f16_f32 v137, v108, v109
	global_store_dwordx4 v214, v[134:137], s[22:23] offset:256
	s_nop 1
	s_add_u32 s22, s2, 0xa0000
	s_addc_u32 s23, s3, 0
	global_load_dwordx4 v[126:129], v214, s[22:23]
	global_load_dwordx4 v[122:125], v214, s[22:23] offset:256
	s_add_u32 s22, s2, 0xb0000
	s_addc_u32 s23, s3, 0
	global_load_dwordx4 v[110:113], v214, s[22:23]
	global_load_dwordx4 v[106:109], v214, s[22:23] offset:256
	s_waitcnt vmcnt(15)
	v_cvt_f32_f16_e32 v210, v138
	v_cvt_f32_f16_sdwa v211, v138 dst_sel:DWORD dst_unused:UNUSED_PAD src0_sel:WORD_1
	v_cvt_f32_f16_e32 v212, v139
	v_cvt_f32_f16_sdwa v213, v139 dst_sel:DWORD dst_unused:UNUSED_PAD src0_sel:WORD_1
	v_pk_fma_f32 v[118:119], v[118:119], v[194:195], v[210:211]
	v_pk_fma_f32 v[120:121], v[120:121], v[196:197], v[212:213]
	v_cvt_f32_f16_e32 v210, v140
	v_cvt_f32_f16_sdwa v211, v140 dst_sel:DWORD dst_unused:UNUSED_PAD src0_sel:WORD_1
	v_cvt_f32_f16_e32 v212, v141
	v_cvt_f32_f16_sdwa v213, v141 dst_sel:DWORD dst_unused:UNUSED_PAD src0_sel:WORD_1
	v_pk_fma_f32 v[114:115], v[114:115], v[198:199], v[210:211]
	v_pk_fma_f32 v[116:117], v[116:117], v[200:201], v[212:213]
	v_cvt_pk_f16_f32 v138, v118, v119
	v_cvt_pk_f16_f32 v139, v120, v121
	v_cvt_pk_f16_f32 v140, v114, v115
	v_cvt_pk_f16_f32 v141, v116, v117
	s_add_u32 s22, s2, 0x10000
	s_addc_u32 s23, s3, 0
	global_store_dwordx4 v214, v[138:141], s[22:23]
	s_waitcnt vmcnt(15)
	v_cvt_f32_f16_e32 v210, v142
	v_cvt_f32_f16_sdwa v211, v142 dst_sel:DWORD dst_unused:UNUSED_PAD src0_sel:WORD_1
	v_cvt_f32_f16_e32 v212, v143
	v_cvt_f32_f16_sdwa v213, v143 dst_sel:DWORD dst_unused:UNUSED_PAD src0_sel:WORD_1
	v_pk_fma_f32 v[102:103], v[102:103], v[202:203], v[210:211]
	v_pk_fma_f32 v[104:105], v[104:105], v[204:205], v[212:213]
	v_cvt_f32_f16_e32 v210, v144
	v_cvt_f32_f16_sdwa v211, v144 dst_sel:DWORD dst_unused:UNUSED_PAD src0_sel:WORD_1
	v_cvt_f32_f16_e32 v212, v145
	v_cvt_f32_f16_sdwa v213, v145 dst_sel:DWORD dst_unused:UNUSED_PAD src0_sel:WORD_1
	v_pk_fma_f32 v[98:99], v[98:99], v[206:207], v[210:211]
	v_pk_fma_f32 v[100:101], v[100:101], v[208:209], v[212:213]
	v_cvt_pk_f16_f32 v142, v102, v103
	v_cvt_pk_f16_f32 v143, v104, v105
	v_cvt_pk_f16_f32 v144, v98, v99
	v_cvt_pk_f16_f32 v145, v100, v101
	global_store_dwordx4 v214, v[142:145], s[22:23] offset:256
	s_waitcnt vmcnt(15)
	v_cvt_f32_f16_e32 v210, v146
	v_cvt_f32_f16_sdwa v211, v146 dst_sel:DWORD dst_unused:UNUSED_PAD src0_sel:WORD_1
	v_cvt_f32_f16_e32 v212, v147
	v_cvt_f32_f16_sdwa v213, v147 dst_sel:DWORD dst_unused:UNUSED_PAD src0_sel:WORD_1
	v_pk_fma_f32 v[94:95], v[94:95], v[194:195], v[210:211]
	v_pk_fma_f32 v[96:97], v[96:97], v[196:197], v[212:213]
	v_cvt_f32_f16_e32 v210, v148
	v_cvt_f32_f16_sdwa v211, v148 dst_sel:DWORD dst_unused:UNUSED_PAD src0_sel:WORD_1
	v_cvt_f32_f16_e32 v212, v149
	v_cvt_f32_f16_sdwa v213, v149 dst_sel:DWORD dst_unused:UNUSED_PAD src0_sel:WORD_1
	v_pk_fma_f32 v[90:91], v[90:91], v[198:199], v[210:211]
	v_pk_fma_f32 v[92:93], v[92:93], v[200:201], v[212:213]
	v_cvt_pk_f16_f32 v146, v94, v95
	v_cvt_pk_f16_f32 v147, v96, v97
	v_cvt_pk_f16_f32 v148, v90, v91
	v_cvt_pk_f16_f32 v149, v92, v93
	s_add_u32 s22, s2, 0x20000
	s_addc_u32 s23, s3, 0
	global_store_dwordx4 v214, v[146:149], s[22:23]
	s_waitcnt vmcnt(15)
	v_cvt_f32_f16_e32 v210, v150
	v_cvt_f32_f16_sdwa v211, v150 dst_sel:DWORD dst_unused:UNUSED_PAD src0_sel:WORD_1
	v_cvt_f32_f16_e32 v212, v151
	v_cvt_f32_f16_sdwa v213, v151 dst_sel:DWORD dst_unused:UNUSED_PAD src0_sel:WORD_1
	v_pk_fma_f32 v[82:83], v[82:83], v[202:203], v[210:211]
	v_pk_fma_f32 v[84:85], v[84:85], v[204:205], v[212:213]
	v_cvt_f32_f16_e32 v210, v152
	v_cvt_f32_f16_sdwa v211, v152 dst_sel:DWORD dst_unused:UNUSED_PAD src0_sel:WORD_1
	v_cvt_f32_f16_e32 v212, v153
	v_cvt_f32_f16_sdwa v213, v153 dst_sel:DWORD dst_unused:UNUSED_PAD src0_sel:WORD_1
	v_pk_fma_f32 v[74:75], v[74:75], v[206:207], v[210:211]
	v_pk_fma_f32 v[76:77], v[76:77], v[208:209], v[212:213]
	v_cvt_pk_f16_f32 v150, v82, v83
	v_cvt_pk_f16_f32 v151, v84, v85
	v_cvt_pk_f16_f32 v152, v74, v75
	v_cvt_pk_f16_f32 v153, v76, v77
	global_store_dwordx4 v214, v[150:153], s[22:23] offset:256
	s_waitcnt vmcnt(15)
	v_cvt_f32_f16_e32 v210, v154
	v_cvt_f32_f16_sdwa v211, v154 dst_sel:DWORD dst_unused:UNUSED_PAD src0_sel:WORD_1
	v_cvt_f32_f16_e32 v212, v155
	v_cvt_f32_f16_sdwa v213, v155 dst_sel:DWORD dst_unused:UNUSED_PAD src0_sel:WORD_1
	v_pk_fma_f32 v[86:87], v[86:87], v[194:195], v[210:211]
	v_pk_fma_f32 v[88:89], v[88:89], v[196:197], v[212:213]
	v_cvt_f32_f16_e32 v210, v156
	v_cvt_f32_f16_sdwa v211, v156 dst_sel:DWORD dst_unused:UNUSED_PAD src0_sel:WORD_1
	v_cvt_f32_f16_e32 v212, v157
	v_cvt_f32_f16_sdwa v213, v157 dst_sel:DWORD dst_unused:UNUSED_PAD src0_sel:WORD_1
	v_pk_fma_f32 v[78:79], v[78:79], v[198:199], v[210:211]
	v_pk_fma_f32 v[80:81], v[80:81], v[200:201], v[212:213]
	v_cvt_pk_f16_f32 v154, v86, v87
	v_cvt_pk_f16_f32 v155, v88, v89
	v_cvt_pk_f16_f32 v156, v78, v79
	v_cvt_pk_f16_f32 v157, v80, v81
	s_add_u32 s22, s2, 0x30000
	s_addc_u32 s23, s3, 0
	global_store_dwordx4 v214, v[154:157], s[22:23]
	s_waitcnt vmcnt(15)
	v_cvt_f32_f16_e32 v210, v158
	v_cvt_f32_f16_sdwa v211, v158 dst_sel:DWORD dst_unused:UNUSED_PAD src0_sel:WORD_1
	v_cvt_f32_f16_e32 v212, v159
	v_cvt_f32_f16_sdwa v213, v159 dst_sel:DWORD dst_unused:UNUSED_PAD src0_sel:WORD_1
	v_pk_fma_f32 v[70:71], v[70:71], v[202:203], v[210:211]
	v_pk_fma_f32 v[72:73], v[72:73], v[204:205], v[212:213]
	v_cvt_f32_f16_e32 v210, v160
	v_cvt_f32_f16_sdwa v211, v160 dst_sel:DWORD dst_unused:UNUSED_PAD src0_sel:WORD_1
	v_cvt_f32_f16_e32 v212, v161
	v_cvt_f32_f16_sdwa v213, v161 dst_sel:DWORD dst_unused:UNUSED_PAD src0_sel:WORD_1
	v_pk_fma_f32 v[66:67], v[66:67], v[206:207], v[210:211]
	v_pk_fma_f32 v[68:69], v[68:69], v[208:209], v[212:213]
	v_cvt_pk_f16_f32 v158, v70, v71
	v_cvt_pk_f16_f32 v159, v72, v73
	v_cvt_pk_f16_f32 v160, v66, v67
	v_cvt_pk_f16_f32 v161, v68, v69
	global_store_dwordx4 v214, v[158:161], s[22:23] offset:256
	s_waitcnt vmcnt(15)
	v_cvt_f32_f16_e32 v210, v166
	v_cvt_f32_f16_sdwa v211, v166 dst_sel:DWORD dst_unused:UNUSED_PAD src0_sel:WORD_1
	v_cvt_f32_f16_e32 v212, v167
	v_cvt_f32_f16_sdwa v213, v167 dst_sel:DWORD dst_unused:UNUSED_PAD src0_sel:WORD_1
	v_pk_fma_f32 v[62:63], v[62:63], v[194:195], v[210:211]
	v_pk_fma_f32 v[64:65], v[64:65], v[196:197], v[212:213]
	v_cvt_f32_f16_e32 v210, v168
	v_cvt_f32_f16_sdwa v211, v168 dst_sel:DWORD dst_unused:UNUSED_PAD src0_sel:WORD_1
	v_cvt_f32_f16_e32 v212, v169
	v_cvt_f32_f16_sdwa v213, v169 dst_sel:DWORD dst_unused:UNUSED_PAD src0_sel:WORD_1
	v_pk_fma_f32 v[58:59], v[58:59], v[198:199], v[210:211]
	v_pk_fma_f32 v[60:61], v[60:61], v[200:201], v[212:213]
	v_cvt_pk_f16_f32 v166, v62, v63
	v_cvt_pk_f16_f32 v167, v64, v65
	v_cvt_pk_f16_f32 v168, v58, v59
	v_cvt_pk_f16_f32 v169, v60, v61
	s_add_u32 s22, s2, 0x80000
	s_addc_u32 s23, s3, 0
	global_store_dwordx4 v214, v[166:169], s[22:23]
	s_waitcnt vmcnt(15)
	v_cvt_f32_f16_e32 v210, v170
	v_cvt_f32_f16_sdwa v211, v170 dst_sel:DWORD dst_unused:UNUSED_PAD src0_sel:WORD_1
	v_cvt_f32_f16_e32 v212, v171
	v_cvt_f32_f16_sdwa v213, v171 dst_sel:DWORD dst_unused:UNUSED_PAD src0_sel:WORD_1
	v_pk_fma_f32 v[54:55], v[54:55], v[202:203], v[210:211]
	v_pk_fma_f32 v[56:57], v[56:57], v[204:205], v[212:213]
	v_cvt_f32_f16_e32 v210, v172
	v_cvt_f32_f16_sdwa v211, v172 dst_sel:DWORD dst_unused:UNUSED_PAD src0_sel:WORD_1
	v_cvt_f32_f16_e32 v212, v173
	v_cvt_f32_f16_sdwa v213, v173 dst_sel:DWORD dst_unused:UNUSED_PAD src0_sel:WORD_1
	v_pk_fma_f32 v[50:51], v[50:51], v[206:207], v[210:211]
	v_pk_fma_f32 v[52:53], v[52:53], v[208:209], v[212:213]
	v_cvt_pk_f16_f32 v170, v54, v55
	v_cvt_pk_f16_f32 v171, v56, v57
	v_cvt_pk_f16_f32 v172, v50, v51
	v_cvt_pk_f16_f32 v173, v52, v53
	global_store_dwordx4 v214, v[170:173], s[22:23] offset:256
	s_waitcnt vmcnt(15)
	v_cvt_f32_f16_e32 v210, v186
	v_cvt_f32_f16_sdwa v211, v186 dst_sel:DWORD dst_unused:UNUSED_PAD src0_sel:WORD_1
	v_cvt_f32_f16_e32 v212, v187
	v_cvt_f32_f16_sdwa v213, v187 dst_sel:DWORD dst_unused:UNUSED_PAD src0_sel:WORD_1
	v_pk_fma_f32 v[46:47], v[46:47], v[194:195], v[210:211]
	v_pk_fma_f32 v[48:49], v[48:49], v[196:197], v[212:213]
	v_cvt_f32_f16_e32 v210, v188
	v_cvt_f32_f16_sdwa v211, v188 dst_sel:DWORD dst_unused:UNUSED_PAD src0_sel:WORD_1
	v_cvt_f32_f16_e32 v212, v189
	v_cvt_f32_f16_sdwa v213, v189 dst_sel:DWORD dst_unused:UNUSED_PAD src0_sel:WORD_1
	v_pk_fma_f32 v[42:43], v[42:43], v[198:199], v[210:211]
	v_pk_fma_f32 v[44:45], v[44:45], v[200:201], v[212:213]
	v_cvt_pk_f16_f32 v186, v46, v47
	v_cvt_pk_f16_f32 v187, v48, v49
	v_cvt_pk_f16_f32 v188, v42, v43
	v_cvt_pk_f16_f32 v189, v44, v45
	s_add_u32 s22, s2, 0x90000
	s_addc_u32 s23, s3, 0
	global_store_dwordx4 v214, v[186:189], s[22:23]
	s_waitcnt vmcnt(15)
	v_cvt_f32_f16_e32 v210, v190
	v_cvt_f32_f16_sdwa v211, v190 dst_sel:DWORD dst_unused:UNUSED_PAD src0_sel:WORD_1
	v_cvt_f32_f16_e32 v212, v191
	v_cvt_f32_f16_sdwa v213, v191 dst_sel:DWORD dst_unused:UNUSED_PAD src0_sel:WORD_1
	v_pk_fma_f32 v[38:39], v[38:39], v[202:203], v[210:211]
	v_pk_fma_f32 v[40:41], v[40:41], v[204:205], v[212:213]
	v_cvt_f32_f16_e32 v210, v192
	v_cvt_f32_f16_sdwa v211, v192 dst_sel:DWORD dst_unused:UNUSED_PAD src0_sel:WORD_1
	v_cvt_f32_f16_e32 v212, v193
	v_cvt_f32_f16_sdwa v213, v193 dst_sel:DWORD dst_unused:UNUSED_PAD src0_sel:WORD_1
	v_pk_fma_f32 v[34:35], v[34:35], v[206:207], v[210:211]
	v_pk_fma_f32 v[36:37], v[36:37], v[208:209], v[212:213]
	v_cvt_pk_f16_f32 v190, v38, v39
	v_cvt_pk_f16_f32 v191, v40, v41
	v_cvt_pk_f16_f32 v192, v34, v35
	v_cvt_pk_f16_f32 v193, v36, v37
	global_store_dwordx4 v214, v[190:193], s[22:23] offset:256
	s_waitcnt vmcnt(13)
	v_cvt_f32_f16_e32 v210, v126
	v_cvt_f32_f16_sdwa v211, v126 dst_sel:DWORD dst_unused:UNUSED_PAD src0_sel:WORD_1
	v_cvt_f32_f16_e32 v212, v127
	v_cvt_f32_f16_sdwa v213, v127 dst_sel:DWORD dst_unused:UNUSED_PAD src0_sel:WORD_1
	v_pk_fma_f32 v[30:31], v[30:31], v[194:195], v[210:211]
	v_pk_fma_f32 v[32:33], v[32:33], v[196:197], v[212:213]
	v_cvt_f32_f16_e32 v210, v128
	v_cvt_f32_f16_sdwa v211, v128 dst_sel:DWORD dst_unused:UNUSED_PAD src0_sel:WORD_1
	v_cvt_f32_f16_e32 v212, v129
	v_cvt_f32_f16_sdwa v213, v129 dst_sel:DWORD dst_unused:UNUSED_PAD src0_sel:WORD_1
	v_pk_fma_f32 v[26:27], v[26:27], v[198:199], v[210:211]
	v_pk_fma_f32 v[28:29], v[28:29], v[200:201], v[212:213]
	v_cvt_pk_f16_f32 v126, v30, v31
	v_cvt_pk_f16_f32 v127, v32, v33
	v_cvt_pk_f16_f32 v128, v26, v27
	v_cvt_pk_f16_f32 v129, v28, v29
	s_add_u32 s22, s2, 0xa0000
	s_addc_u32 s23, s3, 0
	global_store_dwordx4 v214, v[126:129], s[22:23]
	s_waitcnt vmcnt(13)
	v_cvt_f32_f16_e32 v210, v122
	v_cvt_f32_f16_sdwa v211, v122 dst_sel:DWORD dst_unused:UNUSED_PAD src0_sel:WORD_1
	v_cvt_f32_f16_e32 v212, v123
	v_cvt_f32_f16_sdwa v213, v123 dst_sel:DWORD dst_unused:UNUSED_PAD src0_sel:WORD_1
	v_pk_fma_f32 v[22:23], v[22:23], v[202:203], v[210:211]
	v_pk_fma_f32 v[24:25], v[24:25], v[204:205], v[212:213]
	v_cvt_f32_f16_e32 v210, v124
	v_cvt_f32_f16_sdwa v211, v124 dst_sel:DWORD dst_unused:UNUSED_PAD src0_sel:WORD_1
	v_cvt_f32_f16_e32 v212, v125
	v_cvt_f32_f16_sdwa v213, v125 dst_sel:DWORD dst_unused:UNUSED_PAD src0_sel:WORD_1
	v_pk_fma_f32 v[18:19], v[18:19], v[206:207], v[210:211]
	v_pk_fma_f32 v[20:21], v[20:21], v[208:209], v[212:213]
	v_cvt_pk_f16_f32 v122, v22, v23
	v_cvt_pk_f16_f32 v123, v24, v25
	v_cvt_pk_f16_f32 v124, v18, v19
	v_cvt_pk_f16_f32 v125, v20, v21
	global_store_dwordx4 v214, v[122:125], s[22:23] offset:256
	s_waitcnt vmcnt(13)
	v_cvt_f32_f16_e32 v210, v110
	v_cvt_f32_f16_sdwa v211, v110 dst_sel:DWORD dst_unused:UNUSED_PAD src0_sel:WORD_1
	v_cvt_f32_f16_e32 v212, v111
	v_cvt_f32_f16_sdwa v213, v111 dst_sel:DWORD dst_unused:UNUSED_PAD src0_sel:WORD_1
	v_pk_fma_f32 v[14:15], v[14:15], v[194:195], v[210:211]
	v_pk_fma_f32 v[16:17], v[16:17], v[196:197], v[212:213]
	v_cvt_f32_f16_e32 v210, v112
	v_cvt_f32_f16_sdwa v211, v112 dst_sel:DWORD dst_unused:UNUSED_PAD src0_sel:WORD_1
	v_cvt_f32_f16_e32 v212, v113
	v_cvt_f32_f16_sdwa v213, v113 dst_sel:DWORD dst_unused:UNUSED_PAD src0_sel:WORD_1
	v_pk_fma_f32 v[10:11], v[10:11], v[198:199], v[210:211]
	v_pk_fma_f32 v[12:13], v[12:13], v[200:201], v[212:213]
	v_cvt_pk_f16_f32 v110, v14, v15
	v_cvt_pk_f16_f32 v111, v16, v17
	v_cvt_pk_f16_f32 v112, v10, v11
	v_cvt_pk_f16_f32 v113, v12, v13
	s_add_u32 s22, s2, 0xb0000
	s_addc_u32 s23, s3, 0
	global_store_dwordx4 v214, v[110:113], s[22:23]
	s_waitcnt vmcnt(13)
	v_cvt_f32_f16_e32 v210, v106
	v_cvt_f32_f16_sdwa v211, v106 dst_sel:DWORD dst_unused:UNUSED_PAD src0_sel:WORD_1
	v_cvt_f32_f16_e32 v212, v107
	v_cvt_f32_f16_sdwa v213, v107 dst_sel:DWORD dst_unused:UNUSED_PAD src0_sel:WORD_1
	v_pk_fma_f32 v[6:7], v[6:7], v[202:203], v[210:211]
	v_pk_fma_f32 v[8:9], v[8:9], v[204:205], v[212:213]
	v_cvt_f32_f16_e32 v210, v108
	v_cvt_f32_f16_sdwa v211, v108 dst_sel:DWORD dst_unused:UNUSED_PAD src0_sel:WORD_1
	v_cvt_f32_f16_e32 v212, v109
	v_cvt_f32_f16_sdwa v213, v109 dst_sel:DWORD dst_unused:UNUSED_PAD src0_sel:WORD_1
	v_pk_fma_f32 v[2:3], v[2:3], v[206:207], v[210:211]
	v_pk_fma_f32 v[4:5], v[4:5], v[208:209], v[212:213]
	v_cvt_pk_f16_f32 v106, v6, v7
	v_cvt_pk_f16_f32 v107, v8, v9
	v_cvt_pk_f16_f32 v108, v2, v3
	v_cvt_pk_f16_f32 v109, v4, v5
	global_store_dwordx4 v214, v[106:109], s[22:23] offset:256
	s_mov_b64 s[2:3], -1
	s_cbranch_vccnz .LBB0_2402
	s_andn2_b64 vcc, exec, s[4:5]
	s_cbranch_vccnz .LBB0_2401
	s_barrier
	s_branch .LBB0_2401

.LBB0_2795:
	s_andn2_b64 vcc, exec, s[2:3]
	v_lshlrev_b32_e32 v214, 12, v179
	v_lshl_add_u32 v214, v180, 1, v214
	v_lshlrev_b32_e32 v215, 2, v180
	s_lshl_b32 s19, s26, 20
	s_lshl_b32 s21, s62, 9
	s_add_u32 s19, s19, s21
	s_add_u32 s2, s6, s19
	s_addc_u32 s3, s7, 0
	s_lshr_b32 s19, s26, 4
	s_mul_i32 s19, s19, 0x12000
	s_lshl_b32 s21, s62, 10
	s_add_u32 s19, s19, s21
	s_add_u32 s28, s55, s19
	s_addc_u32 s29, s56, 0
	global_load_dwordx4 v[194:197], v215, s[28:29]
	global_load_dwordx4 v[198:201], v215, s[28:29] offset:16
	global_load_dwordx4 v[202:205], v215, s[28:29] offset:512
	global_load_dwordx4 v[206:209], v215, s[28:29] offset:528
	s_add_u32 s28, s2, 0x0
	s_addc_u32 s29, s3, 0
	global_load_dwordx4 v[130:133], v214, s[28:29]
	global_load_dwordx4 v[134:137], v214, s[28:29] offset:256
	s_add_u32 s28, s2, 0x10000
	s_addc_u32 s29, s3, 0
	global_load_dwordx4 v[138:141], v214, s[28:29]
	global_load_dwordx4 v[142:145], v214, s[28:29] offset:256
	s_add_u32 s28, s2, 0x20000
	s_addc_u32 s29, s3, 0
	global_load_dwordx4 v[150:153], v214, s[28:29]
	global_load_dwordx4 v[154:157], v214, s[28:29] offset:256
	s_add_u32 s28, s2, 0x30000
	s_addc_u32 s29, s3, 0
	global_load_dwordx4 v[158:161], v214, s[28:29]
	global_load_dwordx4 v[162:165], v214, s[28:29] offset:256
	s_add_u32 s28, s2, 0x80000
	s_addc_u32 s29, s3, 0
	global_load_dwordx4 v[166:169], v214, s[28:29]
	global_load_dwordx4 v[170:173], v214, s[28:29] offset:256
	s_add_u32 s28, s2, 0x90000
	s_addc_u32 s29, s3, 0
	global_load_dwordx4 v[186:189], v214, s[28:29]
	global_load_dwordx4 v[190:193], v214, s[28:29] offset:256
	s_waitcnt vmcnt(12)
	v_pk_mul_f32 v[194:195], v[194:195], 0.5 op_sel_hi:[1,0]
	v_pk_mul_f32 v[196:197], v[196:197], 0.5 op_sel_hi:[1,0]
	v_pk_mul_f32 v[198:199], v[198:199], 0.5 op_sel_hi:[1,0]
	v_pk_mul_f32 v[200:201], v[200:201], 0.5 op_sel_hi:[1,0]
	v_pk_mul_f32 v[202:203], v[202:203], 0.5 op_sel_hi:[1,0]
	v_pk_mul_f32 v[204:205], v[204:205], 0.5 op_sel_hi:[1,0]
	v_pk_mul_f32 v[206:207], v[206:207], 0.5 op_sel_hi:[1,0]
	v_pk_mul_f32 v[208:209], v[208:209], 0.5 op_sel_hi:[1,0]
	s_waitcnt vmcnt(11)
	v_cvt_f32_f16_e32 v210, v130
	v_cvt_f32_f16_sdwa v211, v130 dst_sel:DWORD dst_unused:UNUSED_PAD src0_sel:WORD_1
	v_cvt_f32_f16_e32 v212, v131
	v_cvt_f32_f16_sdwa v213, v131 dst_sel:DWORD dst_unused:UNUSED_PAD src0_sel:WORD_1
	v_pk_fma_f32 v[126:127], v[126:127], v[194:195], v[210:211]
	v_pk_fma_f32 v[128:129], v[128:129], v[196:197], v[212:213]
	v_cvt_f32_f16_e32 v210, v132
	v_cvt_f32_f16_sdwa v211, v132 dst_sel:DWORD dst_unused:UNUSED_PAD src0_sel:WORD_1
	v_cvt_f32_f16_e32 v212, v133
	v_cvt_f32_f16_sdwa v213, v133 dst_sel:DWORD dst_unused:UNUSED_PAD src0_sel:WORD_1
	v_pk_fma_f32 v[122:123], v[122:123], v[198:199], v[210:211]
	v_pk_fma_f32 v[124:125], v[124:125], v[200:201], v[212:213]
	v_cvt_pk_f16_f32 v130, v126, v127
	v_cvt_pk_f16_f32 v131, v128, v129
	v_cvt_pk_f16_f32 v132, v122, v123
	v_cvt_pk_f16_f32 v133, v124, v125
	s_add_u32 s28, s2, 0x0
	s_addc_u32 s29, s3, 0
	global_store_dwordx4 v214, v[130:133], s[28:29]
	s_waitcnt vmcnt(11)
	v_cvt_f32_f16_e32 v210, v134
	v_cvt_f32_f16_sdwa v211, v134 dst_sel:DWORD dst_unused:UNUSED_PAD src0_sel:WORD_1
	v_cvt_f32_f16_e32 v212, v135
	v_cvt_f32_f16_sdwa v213, v135 dst_sel:DWORD dst_unused:UNUSED_PAD src0_sel:WORD_1
	v_pk_fma_f32 v[114:115], v[114:115], v[202:203], v[210:211]
	v_pk_fma_f32 v[116:117], v[116:117], v[204:205], v[212:213]
	v_cvt_f32_f16_e32 v210, v136
	v_cvt_f32_f16_sdwa v211, v136 dst_sel:DWORD dst_unused:UNUSED_PAD src0_sel:WORD_1
	v_cvt_f32_f16_e32 v212, v137
	v_cvt_f32_f16_sdwa v213, v137 dst_sel:DWORD dst_unused:UNUSED_PAD src0_sel:WORD_1
	v_pk_fma_f32 v[106:107], v[106:107], v[206:207], v[210:211]
	v_pk_fma_f32 v[108:109], v[108:109], v[208:209], v[212:213]
	v_cvt_pk_f16_f32 v134, v114, v115
	v_cvt_pk_f16_f32 v135, v116, v117
	v_cvt_pk_f16_f32 v136, v106, v107
	v_cvt_pk_f16_f32 v137, v108, v109
	global_store_dwordx4 v214, v[134:137], s[28:29] offset:256
	s_nop 1
	s_add_u32 s28, s2, 0xa0000
	s_addc_u32 s29, s3, 0
	global_load_dwordx4 v[126:129], v214, s[28:29]
	global_load_dwordx4 v[122:125], v214, s[28:29] offset:256
	s_add_u32 s28, s2, 0xb0000
	s_addc_u32 s29, s3, 0
	global_load_dwordx4 v[114:117], v214, s[28:29]
	global_load_dwordx4 v[106:109], v214, s[28:29] offset:256
	s_waitcnt vmcnt(15)
	v_cvt_f32_f16_e32 v210, v138
	v_cvt_f32_f16_sdwa v211, v138 dst_sel:DWORD dst_unused:UNUSED_PAD src0_sel:WORD_1
	v_cvt_f32_f16_e32 v212, v139
	v_cvt_f32_f16_sdwa v213, v139 dst_sel:DWORD dst_unused:UNUSED_PAD src0_sel:WORD_1
	v_pk_fma_f32 v[118:119], v[118:119], v[194:195], v[210:211]
	v_pk_fma_f32 v[120:121], v[120:121], v[196:197], v[212:213]
	v_cvt_f32_f16_e32 v210, v140
	v_cvt_f32_f16_sdwa v211, v140 dst_sel:DWORD dst_unused:UNUSED_PAD src0_sel:WORD_1
	v_cvt_f32_f16_e32 v212, v141
	v_cvt_f32_f16_sdwa v213, v141 dst_sel:DWORD dst_unused:UNUSED_PAD src0_sel:WORD_1
	v_pk_fma_f32 v[110:111], v[110:111], v[198:199], v[210:211]
	v_pk_fma_f32 v[112:113], v[112:113], v[200:201], v[212:213]
	v_cvt_pk_f16_f32 v138, v118, v119
	v_cvt_pk_f16_f32 v139, v120, v121
	v_cvt_pk_f16_f32 v140, v110, v111
	v_cvt_pk_f16_f32 v141, v112, v113
	s_add_u32 s28, s2, 0x10000
	s_addc_u32 s29, s3, 0
	global_store_dwordx4 v214, v[138:141], s[28:29]
	s_waitcnt vmcnt(15)
	v_cvt_f32_f16_e32 v210, v142
	v_cvt_f32_f16_sdwa v211, v142 dst_sel:DWORD dst_unused:UNUSED_PAD src0_sel:WORD_1
	v_cvt_f32_f16_e32 v212, v143
	v_cvt_f32_f16_sdwa v213, v143 dst_sel:DWORD dst_unused:UNUSED_PAD src0_sel:WORD_1
	v_pk_fma_f32 v[102:103], v[102:103], v[202:203], v[210:211]
	v_pk_fma_f32 v[104:105], v[104:105], v[204:205], v[212:213]
	v_cvt_f32_f16_e32 v210, v144
	v_cvt_f32_f16_sdwa v211, v144 dst_sel:DWORD dst_unused:UNUSED_PAD src0_sel:WORD_1
	v_cvt_f32_f16_e32 v212, v145
	v_cvt_f32_f16_sdwa v213, v145 dst_sel:DWORD dst_unused:UNUSED_PAD src0_sel:WORD_1
	v_pk_fma_f32 v[98:99], v[98:99], v[206:207], v[210:211]
	v_pk_fma_f32 v[100:101], v[100:101], v[208:209], v[212:213]
	v_cvt_pk_f16_f32 v142, v102, v103
	v_cvt_pk_f16_f32 v143, v104, v105
	v_cvt_pk_f16_f32 v144, v98, v99
	v_cvt_pk_f16_f32 v145, v100, v101
	global_store_dwordx4 v214, v[142:145], s[28:29] offset:256
	s_waitcnt vmcnt(15)
	v_cvt_f32_f16_e32 v210, v150
	v_cvt_f32_f16_sdwa v211, v150 dst_sel:DWORD dst_unused:UNUSED_PAD src0_sel:WORD_1
	v_cvt_f32_f16_e32 v212, v151
	v_cvt_f32_f16_sdwa v213, v151 dst_sel:DWORD dst_unused:UNUSED_PAD src0_sel:WORD_1
	v_pk_fma_f32 v[94:95], v[94:95], v[194:195], v[210:211]
	v_pk_fma_f32 v[96:97], v[96:97], v[196:197], v[212:213]
	v_cvt_f32_f16_e32 v210, v152
	v_cvt_f32_f16_sdwa v211, v152 dst_sel:DWORD dst_unused:UNUSED_PAD src0_sel:WORD_1
	v_cvt_f32_f16_e32 v212, v153
	v_cvt_f32_f16_sdwa v213, v153 dst_sel:DWORD dst_unused:UNUSED_PAD src0_sel:WORD_1
	v_pk_fma_f32 v[90:91], v[90:91], v[198:199], v[210:211]
	v_pk_fma_f32 v[92:93], v[92:93], v[200:201], v[212:213]
	v_cvt_pk_f16_f32 v150, v94, v95
	v_cvt_pk_f16_f32 v151, v96, v97
	v_cvt_pk_f16_f32 v152, v90, v91
	v_cvt_pk_f16_f32 v153, v92, v93
	s_add_u32 s28, s2, 0x20000
	s_addc_u32 s29, s3, 0
	global_store_dwordx4 v214, v[150:153], s[28:29]
	s_waitcnt vmcnt(15)
	v_cvt_f32_f16_e32 v210, v154
	v_cvt_f32_f16_sdwa v211, v154 dst_sel:DWORD dst_unused:UNUSED_PAD src0_sel:WORD_1
	v_cvt_f32_f16_e32 v212, v155
	v_cvt_f32_f16_sdwa v213, v155 dst_sel:DWORD dst_unused:UNUSED_PAD src0_sel:WORD_1
	v_pk_fma_f32 v[82:83], v[82:83], v[202:203], v[210:211]
	v_pk_fma_f32 v[84:85], v[84:85], v[204:205], v[212:213]
	v_cvt_f32_f16_e32 v210, v156
	v_cvt_f32_f16_sdwa v211, v156 dst_sel:DWORD dst_unused:UNUSED_PAD src0_sel:WORD_1
	v_cvt_f32_f16_e32 v212, v157
	v_cvt_f32_f16_sdwa v213, v157 dst_sel:DWORD dst_unused:UNUSED_PAD src0_sel:WORD_1
	v_pk_fma_f32 v[74:75], v[74:75], v[206:207], v[210:211]
	v_pk_fma_f32 v[76:77], v[76:77], v[208:209], v[212:213]
	v_cvt_pk_f16_f32 v154, v82, v83
	v_cvt_pk_f16_f32 v155, v84, v85
	v_cvt_pk_f16_f32 v156, v74, v75
	v_cvt_pk_f16_f32 v157, v76, v77
	global_store_dwordx4 v214, v[154:157], s[28:29] offset:256
	s_waitcnt vmcnt(15)
	v_cvt_f32_f16_e32 v210, v158
	v_cvt_f32_f16_sdwa v211, v158 dst_sel:DWORD dst_unused:UNUSED_PAD src0_sel:WORD_1
	v_cvt_f32_f16_e32 v212, v159
	v_cvt_f32_f16_sdwa v213, v159 dst_sel:DWORD dst_unused:UNUSED_PAD src0_sel:WORD_1
	v_pk_fma_f32 v[86:87], v[86:87], v[194:195], v[210:211]
	v_pk_fma_f32 v[88:89], v[88:89], v[196:197], v[212:213]
	v_cvt_f32_f16_e32 v210, v160
	v_cvt_f32_f16_sdwa v211, v160 dst_sel:DWORD dst_unused:UNUSED_PAD src0_sel:WORD_1
	v_cvt_f32_f16_e32 v212, v161
	v_cvt_f32_f16_sdwa v213, v161 dst_sel:DWORD dst_unused:UNUSED_PAD src0_sel:WORD_1
	v_pk_fma_f32 v[78:79], v[78:79], v[198:199], v[210:211]
	v_pk_fma_f32 v[80:81], v[80:81], v[200:201], v[212:213]
	v_cvt_pk_f16_f32 v158, v86, v87
	v_cvt_pk_f16_f32 v159, v88, v89
	v_cvt_pk_f16_f32 v160, v78, v79
	v_cvt_pk_f16_f32 v161, v80, v81
	s_add_u32 s28, s2, 0x30000
	s_addc_u32 s29, s3, 0
	global_store_dwordx4 v214, v[158:161], s[28:29]
	s_waitcnt vmcnt(15)
	v_cvt_f32_f16_e32 v210, v162
	v_cvt_f32_f16_sdwa v211, v162 dst_sel:DWORD dst_unused:UNUSED_PAD src0_sel:WORD_1
	v_cvt_f32_f16_e32 v212, v163
	v_cvt_f32_f16_sdwa v213, v163 dst_sel:DWORD dst_unused:UNUSED_PAD src0_sel:WORD_1
	v_pk_fma_f32 v[70:71], v[70:71], v[202:203], v[210:211]
	v_pk_fma_f32 v[72:73], v[72:73], v[204:205], v[212:213]
	v_cvt_f32_f16_e32 v210, v164
	v_cvt_f32_f16_sdwa v211, v164 dst_sel:DWORD dst_unused:UNUSED_PAD src0_sel:WORD_1
	v_cvt_f32_f16_e32 v212, v165
	v_cvt_f32_f16_sdwa v213, v165 dst_sel:DWORD dst_unused:UNUSED_PAD src0_sel:WORD_1
	v_pk_fma_f32 v[66:67], v[66:67], v[206:207], v[210:211]
	v_pk_fma_f32 v[68:69], v[68:69], v[208:209], v[212:213]
	v_cvt_pk_f16_f32 v162, v70, v71
	v_cvt_pk_f16_f32 v163, v72, v73
	v_cvt_pk_f16_f32 v164, v66, v67
	v_cvt_pk_f16_f32 v165, v68, v69
	global_store_dwordx4 v214, v[162:165], s[28:29] offset:256
	s_waitcnt vmcnt(15)
	v_cvt_f32_f16_e32 v210, v166
	v_cvt_f32_f16_sdwa v211, v166 dst_sel:DWORD dst_unused:UNUSED_PAD src0_sel:WORD_1
	v_cvt_f32_f16_e32 v212, v167
	v_cvt_f32_f16_sdwa v213, v167 dst_sel:DWORD dst_unused:UNUSED_PAD src0_sel:WORD_1
	v_pk_fma_f32 v[62:63], v[62:63], v[194:195], v[210:211]
	v_pk_fma_f32 v[64:65], v[64:65], v[196:197], v[212:213]
	v_cvt_f32_f16_e32 v210, v168
	v_cvt_f32_f16_sdwa v211, v168 dst_sel:DWORD dst_unused:UNUSED_PAD src0_sel:WORD_1
	v_cvt_f32_f16_e32 v212, v169
	v_cvt_f32_f16_sdwa v213, v169 dst_sel:DWORD dst_unused:UNUSED_PAD src0_sel:WORD_1
	v_pk_fma_f32 v[58:59], v[58:59], v[198:199], v[210:211]
	v_pk_fma_f32 v[60:61], v[60:61], v[200:201], v[212:213]
	v_cvt_pk_f16_f32 v166, v62, v63
	v_cvt_pk_f16_f32 v167, v64, v65
	v_cvt_pk_f16_f32 v168, v58, v59
	v_cvt_pk_f16_f32 v169, v60, v61
	s_add_u32 s28, s2, 0x80000
	s_addc_u32 s29, s3, 0
	global_store_dwordx4 v214, v[166:169], s[28:29]
	s_waitcnt vmcnt(15)
	v_cvt_f32_f16_e32 v210, v170
	v_cvt_f32_f16_sdwa v211, v170 dst_sel:DWORD dst_unused:UNUSED_PAD src0_sel:WORD_1
	v_cvt_f32_f16_e32 v212, v171
	v_cvt_f32_f16_sdwa v213, v171 dst_sel:DWORD dst_unused:UNUSED_PAD src0_sel:WORD_1
	v_pk_fma_f32 v[54:55], v[54:55], v[202:203], v[210:211]
	v_pk_fma_f32 v[56:57], v[56:57], v[204:205], v[212:213]
	v_cvt_f32_f16_e32 v210, v172
	v_cvt_f32_f16_sdwa v211, v172 dst_sel:DWORD dst_unused:UNUSED_PAD src0_sel:WORD_1
	v_cvt_f32_f16_e32 v212, v173
	v_cvt_f32_f16_sdwa v213, v173 dst_sel:DWORD dst_unused:UNUSED_PAD src0_sel:WORD_1
	v_pk_fma_f32 v[50:51], v[50:51], v[206:207], v[210:211]
	v_pk_fma_f32 v[52:53], v[52:53], v[208:209], v[212:213]
	v_cvt_pk_f16_f32 v170, v54, v55
	v_cvt_pk_f16_f32 v171, v56, v57
	v_cvt_pk_f16_f32 v172, v50, v51
	v_cvt_pk_f16_f32 v173, v52, v53
	global_store_dwordx4 v214, v[170:173], s[28:29] offset:256
	s_waitcnt vmcnt(15)
	v_cvt_f32_f16_e32 v210, v186
	v_cvt_f32_f16_sdwa v211, v186 dst_sel:DWORD dst_unused:UNUSED_PAD src0_sel:WORD_1
	v_cvt_f32_f16_e32 v212, v187
	v_cvt_f32_f16_sdwa v213, v187 dst_sel:DWORD dst_unused:UNUSED_PAD src0_sel:WORD_1
	v_pk_fma_f32 v[46:47], v[46:47], v[194:195], v[210:211]
	v_pk_fma_f32 v[48:49], v[48:49], v[196:197], v[212:213]
	v_cvt_f32_f16_e32 v210, v188
	v_cvt_f32_f16_sdwa v211, v188 dst_sel:DWORD dst_unused:UNUSED_PAD src0_sel:WORD_1
	v_cvt_f32_f16_e32 v212, v189
	v_cvt_f32_f16_sdwa v213, v189 dst_sel:DWORD dst_unused:UNUSED_PAD src0_sel:WORD_1
	v_pk_fma_f32 v[42:43], v[42:43], v[198:199], v[210:211]
	v_pk_fma_f32 v[44:45], v[44:45], v[200:201], v[212:213]
	v_cvt_pk_f16_f32 v186, v46, v47
	v_cvt_pk_f16_f32 v187, v48, v49
	v_cvt_pk_f16_f32 v188, v42, v43
	v_cvt_pk_f16_f32 v189, v44, v45
	s_add_u32 s28, s2, 0x90000
	s_addc_u32 s29, s3, 0
	global_store_dwordx4 v214, v[186:189], s[28:29]
	s_waitcnt vmcnt(15)
	v_cvt_f32_f16_e32 v210, v190
	v_cvt_f32_f16_sdwa v211, v190 dst_sel:DWORD dst_unused:UNUSED_PAD src0_sel:WORD_1
	v_cvt_f32_f16_e32 v212, v191
	v_cvt_f32_f16_sdwa v213, v191 dst_sel:DWORD dst_unused:UNUSED_PAD src0_sel:WORD_1
	v_pk_fma_f32 v[38:39], v[38:39], v[202:203], v[210:211]
	v_pk_fma_f32 v[40:41], v[40:41], v[204:205], v[212:213]
	v_cvt_f32_f16_e32 v210, v192
	v_cvt_f32_f16_sdwa v211, v192 dst_sel:DWORD dst_unused:UNUSED_PAD src0_sel:WORD_1
	v_cvt_f32_f16_e32 v212, v193
	v_cvt_f32_f16_sdwa v213, v193 dst_sel:DWORD dst_unused:UNUSED_PAD src0_sel:WORD_1
	v_pk_fma_f32 v[34:35], v[34:35], v[206:207], v[210:211]
	v_pk_fma_f32 v[36:37], v[36:37], v[208:209], v[212:213]
	v_cvt_pk_f16_f32 v190, v38, v39
	v_cvt_pk_f16_f32 v191, v40, v41
	v_cvt_pk_f16_f32 v192, v34, v35
	v_cvt_pk_f16_f32 v193, v36, v37
	global_store_dwordx4 v214, v[190:193], s[28:29] offset:256
	s_waitcnt vmcnt(13)
	v_cvt_f32_f16_e32 v210, v126
	v_cvt_f32_f16_sdwa v211, v126 dst_sel:DWORD dst_unused:UNUSED_PAD src0_sel:WORD_1
	v_cvt_f32_f16_e32 v212, v127
	v_cvt_f32_f16_sdwa v213, v127 dst_sel:DWORD dst_unused:UNUSED_PAD src0_sel:WORD_1
	v_pk_fma_f32 v[30:31], v[30:31], v[194:195], v[210:211]
	v_pk_fma_f32 v[32:33], v[32:33], v[196:197], v[212:213]
	v_cvt_f32_f16_e32 v210, v128
	v_cvt_f32_f16_sdwa v211, v128 dst_sel:DWORD dst_unused:UNUSED_PAD src0_sel:WORD_1
	v_cvt_f32_f16_e32 v212, v129
	v_cvt_f32_f16_sdwa v213, v129 dst_sel:DWORD dst_unused:UNUSED_PAD src0_sel:WORD_1
	v_pk_fma_f32 v[26:27], v[26:27], v[198:199], v[210:211]
	v_pk_fma_f32 v[28:29], v[28:29], v[200:201], v[212:213]
	v_cvt_pk_f16_f32 v126, v30, v31
	v_cvt_pk_f16_f32 v127, v32, v33
	v_cvt_pk_f16_f32 v128, v26, v27
	v_cvt_pk_f16_f32 v129, v28, v29
	s_add_u32 s28, s2, 0xa0000
	s_addc_u32 s29, s3, 0
	global_store_dwordx4 v214, v[126:129], s[28:29]
	s_waitcnt vmcnt(13)
	v_cvt_f32_f16_e32 v210, v122
	v_cvt_f32_f16_sdwa v211, v122 dst_sel:DWORD dst_unused:UNUSED_PAD src0_sel:WORD_1
	v_cvt_f32_f16_e32 v212, v123
	v_cvt_f32_f16_sdwa v213, v123 dst_sel:DWORD dst_unused:UNUSED_PAD src0_sel:WORD_1
	v_pk_fma_f32 v[22:23], v[22:23], v[202:203], v[210:211]
	v_pk_fma_f32 v[24:25], v[24:25], v[204:205], v[212:213]
	v_cvt_f32_f16_e32 v210, v124
	v_cvt_f32_f16_sdwa v211, v124 dst_sel:DWORD dst_unused:UNUSED_PAD src0_sel:WORD_1
	v_cvt_f32_f16_e32 v212, v125
	v_cvt_f32_f16_sdwa v213, v125 dst_sel:DWORD dst_unused:UNUSED_PAD src0_sel:WORD_1
	v_pk_fma_f32 v[18:19], v[18:19], v[206:207], v[210:211]
	v_pk_fma_f32 v[20:21], v[20:21], v[208:209], v[212:213]
	v_cvt_pk_f16_f32 v122, v22, v23
	v_cvt_pk_f16_f32 v123, v24, v25
	v_cvt_pk_f16_f32 v124, v18, v19
	v_cvt_pk_f16_f32 v125, v20, v21
	global_store_dwordx4 v214, v[122:125], s[28:29] offset:256
	s_waitcnt vmcnt(13)
	v_cvt_f32_f16_e32 v210, v114
	v_cvt_f32_f16_sdwa v211, v114 dst_sel:DWORD dst_unused:UNUSED_PAD src0_sel:WORD_1
	v_cvt_f32_f16_e32 v212, v115
	v_cvt_f32_f16_sdwa v213, v115 dst_sel:DWORD dst_unused:UNUSED_PAD src0_sel:WORD_1
	v_pk_fma_f32 v[14:15], v[14:15], v[194:195], v[210:211]
	v_pk_fma_f32 v[16:17], v[16:17], v[196:197], v[212:213]
	v_cvt_f32_f16_e32 v210, v116
	v_cvt_f32_f16_sdwa v211, v116 dst_sel:DWORD dst_unused:UNUSED_PAD src0_sel:WORD_1
	v_cvt_f32_f16_e32 v212, v117
	v_cvt_f32_f16_sdwa v213, v117 dst_sel:DWORD dst_unused:UNUSED_PAD src0_sel:WORD_1
	v_pk_fma_f32 v[10:11], v[10:11], v[198:199], v[210:211]
	v_pk_fma_f32 v[12:13], v[12:13], v[200:201], v[212:213]
	v_cvt_pk_f16_f32 v114, v14, v15
	v_cvt_pk_f16_f32 v115, v16, v17
	v_cvt_pk_f16_f32 v116, v10, v11
	v_cvt_pk_f16_f32 v117, v12, v13
	s_add_u32 s28, s2, 0xb0000
	s_addc_u32 s29, s3, 0
	global_store_dwordx4 v214, v[114:117], s[28:29]
	s_waitcnt vmcnt(13)
	v_cvt_f32_f16_e32 v210, v106
	v_cvt_f32_f16_sdwa v211, v106 dst_sel:DWORD dst_unused:UNUSED_PAD src0_sel:WORD_1
	v_cvt_f32_f16_e32 v212, v107
	v_cvt_f32_f16_sdwa v213, v107 dst_sel:DWORD dst_unused:UNUSED_PAD src0_sel:WORD_1
	v_pk_fma_f32 v[6:7], v[6:7], v[202:203], v[210:211]
	v_pk_fma_f32 v[8:9], v[8:9], v[204:205], v[212:213]
	v_cvt_f32_f16_e32 v210, v108
	v_cvt_f32_f16_sdwa v211, v108 dst_sel:DWORD dst_unused:UNUSED_PAD src0_sel:WORD_1
	v_cvt_f32_f16_e32 v212, v109
	v_cvt_f32_f16_sdwa v213, v109 dst_sel:DWORD dst_unused:UNUSED_PAD src0_sel:WORD_1
	v_pk_fma_f32 v[2:3], v[2:3], v[206:207], v[210:211]
	v_pk_fma_f32 v[4:5], v[4:5], v[208:209], v[212:213]
	v_cvt_pk_f16_f32 v106, v6, v7
	v_cvt_pk_f16_f32 v107, v8, v9
	v_cvt_pk_f16_f32 v108, v2, v3
	v_cvt_pk_f16_f32 v109, v4, v5
	global_store_dwordx4 v214, v[106:109], s[28:29] offset:256
	s_mov_b64 s[2:3], -1
	s_cbranch_vccnz .LBB0_2784
	s_andn2_b64 vcc, exec, s[4:5]
	s_cbranch_vccnz .LBB0_2783
	s_barrier
	s_branch .LBB0_2783
